# GEMM loop: scalar address arithmetic of the load segments moved into the MFMA segments (SALU between MFMAs)
# baseline (speedup 1.0000x reference)
.LBB0_176:
	s_mov_b32 m0, s55
	s_nop 0
	global_load_lds_dwordx4 v194, s[100:101]
	s_mov_b32 m0, s67
	s_nop 0
	global_load_lds_dwordx4 v196, s[100:101]
	v_add_u32_e32 v130, 0x10000, v243
	v_add_u32_e32 v142, 0x14000, v243
	ds_read_b128 v[146:149], v130
	ds_read_b128 v[150:153], v130 offset:1024
	ds_read_b128 v[154:157], v130 offset:2048
	ds_read_b128 v[158:161], v130 offset:3072
	ds_read_b128 v[130:133], v142
	ds_read_b128 v[134:137], v142 offset:1024
	ds_read_b128 v[138:141], v142 offset:2048
	ds_read_b128 v[142:145], v142 offset:3072
	v_lshl_add_u64 v[246:247], v[234:235], 0, s[80:81]
	s_add_i32 m0, s8, 0xc000
	s_waitcnt lgkmcnt(0)
	ds_read_b128 v[174:177], v244
	ds_read_b128 v[190:193], v244 offset:1024
	ds_read_b128 v[170:173], v244 offset:2048
	ds_read_b128 v[186:189], v244 offset:3072
	ds_read_b128 v[166:169], v244 offset:4096
	ds_read_b128 v[182:185], v244 offset:5120
	ds_read_b128 v[162:165], v244 offset:6144
	ds_read_b128 v[178:181], v244 offset:7168
	global_load_lds_dwordx4 v[246:247], off
	v_lshl_add_u64 v[246:247], v[236:237], 0, s[80:81]
	s_add_i32 m0, s8, 0xe000
	s_nop 0
	global_load_lds_dwordx4 v[246:247], off
	s_waitcnt vmcnt(8)
	s_waitcnt lgkmcnt(0)
	s_barrier
	s_setprio 1
	s_waitcnt lgkmcnt(0)
	v_mfma_f32_16x16x32_bf16 v[118:121], v[146:149], v[174:177], v[118:121]
	v_mfma_f32_16x16x32_bf16 v[126:129], v[154:157], v[174:177], v[126:129]
	v_mfma_f32_16x16x32_bf16 v[102:105], v[146:149], v[170:173], v[102:105]
	v_mfma_f32_16x16x32_bf16 v[110:113], v[154:157], v[170:173], v[110:113]
	v_mfma_f32_16x16x32_bf16 v[86:89], v[146:149], v[166:169], v[86:89]
	v_mfma_f32_16x16x32_bf16 v[94:97], v[154:157], v[166:169], v[94:97]
	v_mfma_f32_16x16x32_bf16 v[70:73], v[146:149], v[162:165], v[70:73]
	v_mfma_f32_16x16x32_bf16 v[78:81], v[154:157], v[162:165], v[78:81]
	v_mfma_f32_16x16x32_bf16 v[118:121], v[150:153], v[190:193], v[118:121]
	v_mfma_f32_16x16x32_bf16 v[126:129], v[158:161], v[190:193], v[126:129]
	v_mfma_f32_16x16x32_bf16 v[102:105], v[150:153], v[186:189], v[102:105]
	v_mfma_f32_16x16x32_bf16 v[110:113], v[158:161], v[186:189], v[110:113]
	v_mfma_f32_16x16x32_bf16 v[86:89], v[150:153], v[182:185], v[86:89]
	v_mfma_f32_16x16x32_bf16 v[94:97], v[158:161], v[182:185], v[94:97]
	v_mfma_f32_16x16x32_bf16 v[70:73], v[150:153], v[178:181], v[70:73]
	v_mfma_f32_16x16x32_bf16 v[78:81], v[158:161], v[178:181], v[78:81]
	s_setprio 0
	s_setprio 1
	s_add_u32 s82, s0, s80
	s_addc_u32 s83, s1, s81
	s_add_u32 s84, s82, 0x460000
	s_addc_u32 s85, s83, 0
	s_cmp_eq_u32 s80, 0x41a0000
	s_cselect_b64 s[86:87], -1, 0
	s_and_b64 s[82:83], s[86:87], exec
	s_cselect_b32 s83, s71, s97
	s_cselect_b32 s82, s73, s79
	s_cselect_b32 s85, s22, s85
	s_cselect_b32 s84, s69, s84
	v_mfma_f32_16x16x32_bf16 v[122:125], v[130:133], v[174:177], v[122:125]
	v_mfma_f32_16x16x32_bf16 v[114:117], v[138:141], v[174:177], v[114:117]
	v_mfma_f32_16x16x32_bf16 v[106:109], v[130:133], v[170:173], v[106:109]
	v_mfma_f32_16x16x32_bf16 v[98:101], v[138:141], v[170:173], v[98:101]
	v_mfma_f32_16x16x32_bf16 v[90:93], v[130:133], v[166:169], v[90:93]
	v_mfma_f32_16x16x32_bf16 v[82:85], v[138:141], v[166:169], v[82:85]
	v_mfma_f32_16x16x32_bf16 v[74:77], v[130:133], v[162:165], v[74:77]
	v_mfma_f32_16x16x32_bf16 v[66:69], v[138:141], v[162:165], v[66:69]
	v_mfma_f32_16x16x32_bf16 v[122:125], v[134:137], v[190:193], v[122:125]
	v_mfma_f32_16x16x32_bf16 v[114:117], v[142:145], v[190:193], v[114:117]
	v_mfma_f32_16x16x32_bf16 v[106:109], v[134:137], v[186:189], v[106:109]
	v_mfma_f32_16x16x32_bf16 v[98:101], v[142:145], v[186:189], v[98:101]
	v_mfma_f32_16x16x32_bf16 v[90:93], v[134:137], v[182:185], v[90:93]
	v_mfma_f32_16x16x32_bf16 v[82:85], v[142:145], v[182:185], v[82:85]
	v_mfma_f32_16x16x32_bf16 v[74:77], v[134:137], v[178:181], v[74:77]
	v_mfma_f32_16x16x32_bf16 v[66:69], v[142:145], v[178:181], v[66:69]
	s_setprio 0
	s_barrier
	v_cndmask_b32_e64 v246, 0, 1, s[50:51]
	v_cmp_ne_u32_e64 s[48:49], 1, v246
	s_andn2_b64 vcc, exec, s[50:51]
	s_cbranch_vccnz .LBB0_178
	ds_read_b128 v[174:177], v244 offset:16384
	ds_read_b128 v[190:193], v244 offset:17408
	ds_read_b128 v[170:173], v244 offset:18432
	ds_read_b128 v[186:189], v244 offset:19456
	ds_read_b128 v[166:169], v244 offset:20480
	ds_read_b128 v[182:185], v244 offset:21504
	ds_read_b128 v[162:165], v244 offset:22528
	ds_read_b128 v[178:181], v244 offset:23552
.LBB0_178:
	s_mov_b32 m0, s9
	s_add_u32 vcc_lo, s82, 0x4000
	global_load_lds_dwordx4 v194, s[82:83]
	s_mov_b32 m0, s10
	s_addc_u32 vcc_hi, s83, 0
	global_load_lds_dwordx4 v196, s[82:83]
	s_mov_b32 m0, s11
	s_nop 0
	global_load_lds_dwordx4 v194, vcc
	v_lshl_add_u64 v[246:247], vcc, 0, v[196:197]
	s_mov_b32 m0, s12
	s_and_b64 vcc, exec, s[48:49]
	global_load_lds_dwordx4 v[246:247], off
	s_mov_b64 s[98:99], s[84:85]
	s_waitcnt vmcnt(6)
	s_waitcnt lgkmcnt(0)
	s_barrier
	s_cbranch_vccnz .LBB0_180
	s_setprio 1
	s_waitcnt lgkmcnt(0)
	v_mfma_f32_16x16x32_bf16 v[54:57], v[146:149], v[174:177], v[54:57]
	v_mfma_f32_16x16x32_bf16 v[62:65], v[154:157], v[174:177], v[62:65]
	v_mfma_f32_16x16x32_bf16 v[38:41], v[146:149], v[170:173], v[38:41]
	v_mfma_f32_16x16x32_bf16 v[46:49], v[154:157], v[170:173], v[46:49]
	v_mfma_f32_16x16x32_bf16 v[22:25], v[146:149], v[166:169], v[22:25]
	v_mfma_f32_16x16x32_bf16 v[30:33], v[154:157], v[166:169], v[30:33]
	v_mfma_f32_16x16x32_bf16 v[10:13], v[146:149], v[162:165], v[10:13]
	v_mfma_f32_16x16x32_bf16 v[14:17], v[154:157], v[162:165], v[14:17]
	v_mfma_f32_16x16x32_bf16 v[54:57], v[150:153], v[190:193], v[54:57]
	v_mfma_f32_16x16x32_bf16 v[62:65], v[158:161], v[190:193], v[62:65]
	v_mfma_f32_16x16x32_bf16 v[38:41], v[150:153], v[186:189], v[38:41]
	v_mfma_f32_16x16x32_bf16 v[46:49], v[158:161], v[186:189], v[46:49]
	v_mfma_f32_16x16x32_bf16 v[22:25], v[150:153], v[182:185], v[22:25]
	v_mfma_f32_16x16x32_bf16 v[30:33], v[158:161], v[182:185], v[30:33]
	v_mfma_f32_16x16x32_bf16 v[10:13], v[150:153], v[178:181], v[10:13]
	v_mfma_f32_16x16x32_bf16 v[14:17], v[158:161], v[178:181], v[14:17]
	s_setprio 0
	s_setprio 1
	v_mfma_f32_16x16x32_bf16 v[58:61], v[130:133], v[174:177], v[58:61]
	v_mfma_f32_16x16x32_bf16 v[50:53], v[138:141], v[174:177], v[50:53]
	v_mfma_f32_16x16x32_bf16 v[42:45], v[130:133], v[170:173], v[42:45]
	v_mfma_f32_16x16x32_bf16 v[34:37], v[138:141], v[170:173], v[34:37]
	v_mfma_f32_16x16x32_bf16 v[26:29], v[130:133], v[166:169], v[26:29]
	v_mfma_f32_16x16x32_bf16 v[18:21], v[138:141], v[166:169], v[18:21]
	v_mfma_f32_16x16x32_bf16 v[6:9], v[130:133], v[162:165], v[6:9]
	v_mfma_f32_16x16x32_bf16 v[2:5], v[138:141], v[162:165], v[2:5]
	v_mfma_f32_16x16x32_bf16 v[58:61], v[134:137], v[190:193], v[58:61]
	v_mfma_f32_16x16x32_bf16 v[50:53], v[142:145], v[190:193], v[50:53]
	v_mfma_f32_16x16x32_bf16 v[42:45], v[134:137], v[186:189], v[42:45]
	v_mfma_f32_16x16x32_bf16 v[34:37], v[142:145], v[186:189], v[34:37]
	v_mfma_f32_16x16x32_bf16 v[26:29], v[134:137], v[182:185], v[26:29]
	v_mfma_f32_16x16x32_bf16 v[18:21], v[142:145], v[182:185], v[18:21]
	v_mfma_f32_16x16x32_bf16 v[6:9], v[134:137], v[178:181], v[6:9]
	v_mfma_f32_16x16x32_bf16 v[2:5], v[142:145], v[178:181], v[2:5]
	s_setprio 0
.LBB0_180:
	s_and_b64 vcc, s[46:47], s[86:87]
	v_cndmask_b32_e64 v131, v233, 0, vcc
	v_cndmask_b32_e32 v130, v232, v198, vcc
	v_lshl_add_u64 v[246:247], s[84:85], 0, v[130:131]
	s_barrier
	s_mov_b32 m0, s8
	s_nop 0
	global_load_lds_dwordx4 v194, s[98:99]
	s_mov_b32 m0, s13
	s_nop 0
	global_load_lds_dwordx4 v196, s[98:99]
	v_add_u32_e32 v130, 0x18000, v243
	v_add_u32_e32 v142, 0x1c000, v243
	ds_read_b128 v[146:149], v130
	ds_read_b128 v[150:153], v130 offset:1024
	ds_read_b128 v[154:157], v130 offset:2048
	ds_read_b128 v[158:161], v130 offset:3072
	ds_read_b128 v[130:133], v142
	ds_read_b128 v[134:137], v142 offset:1024
	ds_read_b128 v[138:141], v142 offset:2048
	ds_read_b128 v[142:145], v142 offset:3072
	s_mov_b32 m0, s14
	v_lshl_add_u64 v[248:249], v[246:247], 0, v[194:195]
	s_waitcnt lgkmcnt(0)
	ds_read_b128 v[174:177], v244 offset:32768
	ds_read_b128 v[190:193], v244 offset:33792
	ds_read_b128 v[170:173], v244 offset:34816
	ds_read_b128 v[186:189], v244 offset:35840
	ds_read_b128 v[166:169], v244 offset:36864
	ds_read_b128 v[182:185], v244 offset:37888
	ds_read_b128 v[162:165], v244 offset:38912
	ds_read_b128 v[178:181], v244 offset:39936
	global_load_lds_dwordx4 v[248:249], off
	v_lshl_add_u64 v[246:247], v[246:247], 0, v[196:197]
	s_mov_b32 m0, s15
	s_nop 0
	global_load_lds_dwordx4 v[246:247], off
	s_waitcnt vmcnt(8)
	s_waitcnt lgkmcnt(0)
	s_barrier
	s_setprio 1
	s_waitcnt lgkmcnt(0)
	v_mfma_f32_16x16x32_bf16 v[118:121], v[146:149], v[174:177], v[118:121]
	v_mfma_f32_16x16x32_bf16 v[126:129], v[154:157], v[174:177], v[126:129]
	v_mfma_f32_16x16x32_bf16 v[102:105], v[146:149], v[170:173], v[102:105]
	v_mfma_f32_16x16x32_bf16 v[110:113], v[154:157], v[170:173], v[110:113]
	v_mfma_f32_16x16x32_bf16 v[86:89], v[146:149], v[166:169], v[86:89]
	v_mfma_f32_16x16x32_bf16 v[94:97], v[154:157], v[166:169], v[94:97]
	v_mfma_f32_16x16x32_bf16 v[70:73], v[146:149], v[162:165], v[70:73]
	v_mfma_f32_16x16x32_bf16 v[78:81], v[154:157], v[162:165], v[78:81]
	v_mfma_f32_16x16x32_bf16 v[118:121], v[150:153], v[190:193], v[118:121]
	v_mfma_f32_16x16x32_bf16 v[126:129], v[158:161], v[190:193], v[126:129]
	v_mfma_f32_16x16x32_bf16 v[102:105], v[150:153], v[186:189], v[102:105]
	v_mfma_f32_16x16x32_bf16 v[110:113], v[158:161], v[186:189], v[110:113]
	v_mfma_f32_16x16x32_bf16 v[86:89], v[150:153], v[182:185], v[86:89]
	v_mfma_f32_16x16x32_bf16 v[94:97], v[158:161], v[182:185], v[94:97]
	v_mfma_f32_16x16x32_bf16 v[70:73], v[150:153], v[178:181], v[70:73]
	v_mfma_f32_16x16x32_bf16 v[78:81], v[158:161], v[178:181], v[78:81]
	s_setprio 0
	s_setprio 1
	s_add_u32 s86, s82, 0x120000
	s_addc_u32 s87, s83, 0
	s_add_u32 s84, s84, 0x230000
	s_addc_u32 s85, s85, 0
	v_mfma_f32_16x16x32_bf16 v[122:125], v[130:133], v[174:177], v[122:125]
	v_mfma_f32_16x16x32_bf16 v[114:117], v[138:141], v[174:177], v[114:117]
	v_mfma_f32_16x16x32_bf16 v[106:109], v[130:133], v[170:173], v[106:109]
	v_mfma_f32_16x16x32_bf16 v[98:101], v[138:141], v[170:173], v[98:101]
	v_mfma_f32_16x16x32_bf16 v[90:93], v[130:133], v[166:169], v[90:93]
	v_mfma_f32_16x16x32_bf16 v[82:85], v[138:141], v[166:169], v[82:85]
	v_mfma_f32_16x16x32_bf16 v[74:77], v[130:133], v[162:165], v[74:77]
	v_mfma_f32_16x16x32_bf16 v[66:69], v[138:141], v[162:165], v[66:69]
	v_mfma_f32_16x16x32_bf16 v[122:125], v[134:137], v[190:193], v[122:125]
	v_mfma_f32_16x16x32_bf16 v[114:117], v[142:145], v[190:193], v[114:117]
	v_mfma_f32_16x16x32_bf16 v[106:109], v[134:137], v[186:189], v[106:109]
	v_mfma_f32_16x16x32_bf16 v[98:101], v[142:145], v[186:189], v[98:101]
	v_mfma_f32_16x16x32_bf16 v[90:93], v[134:137], v[182:185], v[90:93]
	v_mfma_f32_16x16x32_bf16 v[82:85], v[142:145], v[182:185], v[82:85]
	v_mfma_f32_16x16x32_bf16 v[74:77], v[134:137], v[178:181], v[74:77]
	v_mfma_f32_16x16x32_bf16 v[66:69], v[142:145], v[178:181], v[66:69]
	s_setprio 0
	s_barrier
	s_and_b64 vcc, exec, s[48:49]
	s_cbranch_vccnz .LBB0_182
	ds_read_b128 v[174:177], v244 offset:49152
	ds_read_b128 v[190:193], v244 offset:50176
	ds_read_b128 v[170:173], v244 offset:51200
	ds_read_b128 v[186:189], v244 offset:52224
	ds_read_b128 v[166:169], v244 offset:53248
	ds_read_b128 v[182:185], v244 offset:54272
	ds_read_b128 v[162:165], v244 offset:55296
	ds_read_b128 v[178:181], v244 offset:56320
.LBB0_182:
	s_mov_b32 m0, s17
	s_add_u32 s82, s82, 0x124000
	global_load_lds_dwordx4 v194, s[86:87]
	s_mov_b32 m0, s54
	s_addc_u32 s83, s83, 0
	global_load_lds_dwordx4 v196, s[86:87]
	s_mov_b32 m0, s89
	s_and_b64 vcc, exec, s[48:49]
	global_load_lds_dwordx4 v194, s[82:83]
	s_mov_b32 m0, s90
	s_nop 0
	global_load_lds_dwordx4 v196, s[82:83]
	s_mov_b64 s[100:101], s[84:85]
	s_waitcnt vmcnt(6)
	s_waitcnt lgkmcnt(0)
	s_barrier
	s_cbranch_vccnz .LBB0_175
	s_setprio 1
	s_waitcnt lgkmcnt(0)
	v_mfma_f32_16x16x32_bf16 v[54:57], v[146:149], v[174:177], v[54:57]
	v_mfma_f32_16x16x32_bf16 v[62:65], v[154:157], v[174:177], v[62:65]
	v_mfma_f32_16x16x32_bf16 v[38:41], v[146:149], v[170:173], v[38:41]
	v_mfma_f32_16x16x32_bf16 v[46:49], v[154:157], v[170:173], v[46:49]
	v_mfma_f32_16x16x32_bf16 v[22:25], v[146:149], v[166:169], v[22:25]
	v_mfma_f32_16x16x32_bf16 v[30:33], v[154:157], v[166:169], v[30:33]
	v_mfma_f32_16x16x32_bf16 v[10:13], v[146:149], v[162:165], v[10:13]
	v_mfma_f32_16x16x32_bf16 v[14:17], v[154:157], v[162:165], v[14:17]
	v_mfma_f32_16x16x32_bf16 v[54:57], v[150:153], v[190:193], v[54:57]
	v_mfma_f32_16x16x32_bf16 v[62:65], v[158:161], v[190:193], v[62:65]
	v_mfma_f32_16x16x32_bf16 v[38:41], v[150:153], v[186:189], v[38:41]
	v_mfma_f32_16x16x32_bf16 v[46:49], v[158:161], v[186:189], v[46:49]
	v_mfma_f32_16x16x32_bf16 v[22:25], v[150:153], v[182:185], v[22:25]
	v_mfma_f32_16x16x32_bf16 v[30:33], v[158:161], v[182:185], v[30:33]
	v_mfma_f32_16x16x32_bf16 v[10:13], v[150:153], v[178:181], v[10:13]
	v_mfma_f32_16x16x32_bf16 v[14:17], v[158:161], v[178:181], v[14:17]
	s_setprio 0
	s_setprio 1
	v_mfma_f32_16x16x32_bf16 v[58:61], v[130:133], v[174:177], v[58:61]
	v_mfma_f32_16x16x32_bf16 v[50:53], v[138:141], v[174:177], v[50:53]
	v_mfma_f32_16x16x32_bf16 v[42:45], v[130:133], v[170:173], v[42:45]
	v_mfma_f32_16x16x32_bf16 v[34:37], v[138:141], v[170:173], v[34:37]
	v_mfma_f32_16x16x32_bf16 v[26:29], v[130:133], v[166:169], v[26:29]
	v_mfma_f32_16x16x32_bf16 v[18:21], v[138:141], v[166:169], v[18:21]
	v_mfma_f32_16x16x32_bf16 v[6:9], v[130:133], v[162:165], v[6:9]
	v_mfma_f32_16x16x32_bf16 v[2:5], v[138:141], v[162:165], v[2:5]
	v_mfma_f32_16x16x32_bf16 v[58:61], v[134:137], v[190:193], v[58:61]
	v_mfma_f32_16x16x32_bf16 v[50:53], v[142:145], v[190:193], v[50:53]
	v_mfma_f32_16x16x32_bf16 v[42:45], v[134:137], v[186:189], v[42:45]
	v_mfma_f32_16x16x32_bf16 v[34:37], v[142:145], v[186:189], v[34:37]
	v_mfma_f32_16x16x32_bf16 v[26:29], v[134:137], v[182:185], v[26:29]
	v_mfma_f32_16x16x32_bf16 v[18:21], v[142:145], v[182:185], v[18:21]
	v_mfma_f32_16x16x32_bf16 v[6:9], v[134:137], v[178:181], v[6:9]
	v_mfma_f32_16x16x32_bf16 v[2:5], v[142:145], v[178:181], v[2:5]
	s_setprio 0
	s_branch .LBB0_175

.LBB0_559:
	s_mov_b32 m0, s55
	s_nop 0
	global_load_lds_dwordx4 v194, s[100:101]
	s_mov_b32 m0, s67
	s_nop 0
	global_load_lds_dwordx4 v196, s[100:101]
	ds_read_b128 v[146:149], v227
	ds_read_b128 v[150:153], v227 offset:1024
	ds_read_b128 v[154:157], v227 offset:2048
	ds_read_b128 v[158:161], v227 offset:3072
	ds_read_b128 v[130:133], v228
	ds_read_b128 v[134:137], v228 offset:1024
	ds_read_b128 v[138:141], v228 offset:2048
	ds_read_b128 v[142:145], v228 offset:3072
	v_lshl_add_u64 v[234:235], v[216:217], 0, s[58:59]
	s_add_i32 m0, s8, 0xc000
	s_waitcnt lgkmcnt(0)
	ds_read_b128 v[174:177], v229
	ds_read_b128 v[190:193], v229 offset:1024
	ds_read_b128 v[170:173], v229 offset:2048
	ds_read_b128 v[186:189], v229 offset:3072
	ds_read_b128 v[166:169], v229 offset:4096
	ds_read_b128 v[182:185], v229 offset:5120
	ds_read_b128 v[162:165], v229 offset:6144
	ds_read_b128 v[178:181], v229 offset:7168
	global_load_lds_dwordx4 v[234:235], off
	v_lshl_add_u64 v[234:235], v[218:219], 0, s[58:59]
	s_add_i32 m0, s8, 0xe000
	s_nop 0
	global_load_lds_dwordx4 v[234:235], off
	s_waitcnt vmcnt(8)
	s_waitcnt lgkmcnt(0)
	s_barrier
	s_setprio 1
	s_waitcnt lgkmcnt(0)
	v_mfma_f32_16x16x32_bf16 v[126:129], v[146:149], v[174:177], v[126:129]
	v_mfma_f32_16x16x32_bf16 v[122:125], v[154:157], v[174:177], v[122:125]
	v_mfma_f32_16x16x32_bf16 v[110:113], v[146:149], v[170:173], v[110:113]
	v_mfma_f32_16x16x32_bf16 v[106:109], v[154:157], v[170:173], v[106:109]
	v_mfma_f32_16x16x32_bf16 v[94:97], v[146:149], v[166:169], v[94:97]
	v_mfma_f32_16x16x32_bf16 v[90:93], v[154:157], v[166:169], v[90:93]
	v_mfma_f32_16x16x32_bf16 v[78:81], v[146:149], v[162:165], v[78:81]
	v_mfma_f32_16x16x32_bf16 v[74:77], v[154:157], v[162:165], v[74:77]
	v_mfma_f32_16x16x32_bf16 v[126:129], v[150:153], v[190:193], v[126:129]
	v_mfma_f32_16x16x32_bf16 v[122:125], v[158:161], v[190:193], v[122:125]
	v_mfma_f32_16x16x32_bf16 v[110:113], v[150:153], v[186:189], v[110:113]
	v_mfma_f32_16x16x32_bf16 v[106:109], v[158:161], v[186:189], v[106:109]
	v_mfma_f32_16x16x32_bf16 v[94:97], v[150:153], v[182:185], v[94:97]
	v_mfma_f32_16x16x32_bf16 v[90:93], v[158:161], v[182:185], v[90:93]
	v_mfma_f32_16x16x32_bf16 v[78:81], v[150:153], v[178:181], v[78:81]
	v_mfma_f32_16x16x32_bf16 v[74:77], v[158:161], v[178:181], v[74:77]
	s_setprio 0
	s_setprio 1
	s_add_u32 s60, s56, s58
	s_addc_u32 s61, s57, s59
	s_add_u32 s62, s60, 0x440000
	s_addc_u32 s63, s61, 0
	s_cmp_eq_u32 s58, 0x3fc0000
	s_cselect_b64 s[68:69], -1, 0
	s_and_b64 s[60:61], s[68:69], exec
	s_cselect_b32 s61, s37, s72
	s_cselect_b32 s60, s47, s53
	s_cselect_b32 s63, s1, s63
	s_cselect_b32 s62, s24, s62
	v_mfma_f32_16x16x32_bf16 v[118:121], v[130:133], v[174:177], v[118:121]
	v_mfma_f32_16x16x32_bf16 v[114:117], v[138:141], v[174:177], v[114:117]
	v_mfma_f32_16x16x32_bf16 v[102:105], v[130:133], v[170:173], v[102:105]
	v_mfma_f32_16x16x32_bf16 v[98:101], v[138:141], v[170:173], v[98:101]
	v_mfma_f32_16x16x32_bf16 v[86:89], v[130:133], v[166:169], v[86:89]
	v_mfma_f32_16x16x32_bf16 v[82:85], v[138:141], v[166:169], v[82:85]
	v_mfma_f32_16x16x32_bf16 v[70:73], v[130:133], v[162:165], v[70:73]
	v_mfma_f32_16x16x32_bf16 v[66:69], v[138:141], v[162:165], v[66:69]
	v_mfma_f32_16x16x32_bf16 v[118:121], v[134:137], v[190:193], v[118:121]
	v_mfma_f32_16x16x32_bf16 v[114:117], v[142:145], v[190:193], v[114:117]
	v_mfma_f32_16x16x32_bf16 v[102:105], v[134:137], v[186:189], v[102:105]
	v_mfma_f32_16x16x32_bf16 v[98:101], v[142:145], v[186:189], v[98:101]
	v_mfma_f32_16x16x32_bf16 v[86:89], v[134:137], v[182:185], v[86:89]
	v_mfma_f32_16x16x32_bf16 v[82:85], v[142:145], v[182:185], v[82:85]
	v_mfma_f32_16x16x32_bf16 v[70:73], v[134:137], v[178:181], v[70:73]
	v_mfma_f32_16x16x32_bf16 v[66:69], v[142:145], v[178:181], v[66:69]
	s_setprio 0
	s_barrier
	v_cmp_ne_u32_e64 s[42:43], 1, v233
	s_andn2_b64 vcc, exec, s[44:45]
	s_cbranch_vccnz .LBB0_561
	ds_read_b128 v[174:177], v229 offset:16384
	ds_read_b128 v[190:193], v229 offset:17408
	ds_read_b128 v[170:173], v229 offset:18432
	ds_read_b128 v[186:189], v229 offset:19456
	ds_read_b128 v[166:169], v229 offset:20480
	ds_read_b128 v[182:185], v229 offset:21504
	ds_read_b128 v[162:165], v229 offset:22528
	ds_read_b128 v[178:181], v229 offset:23552
.LBB0_561:
	s_mov_b32 m0, s9
	s_add_u32 s74, s60, 0x4000
	global_load_lds_dwordx4 v194, s[60:61]
	s_mov_b32 m0, s10
	s_addc_u32 s75, s61, 0
	global_load_lds_dwordx4 v196, s[60:61]
	s_mov_b32 m0, s11
	s_and_b64 vcc, exec, s[42:43]
	global_load_lds_dwordx4 v194, s[74:75]
	s_mov_b32 m0, s12
	s_nop 0
	global_load_lds_dwordx4 v196, s[74:75]
	s_mov_b64 s[98:99], s[62:63]
	s_waitcnt vmcnt(6)
	s_waitcnt lgkmcnt(0)
	s_barrier
	s_cbranch_vccnz .LBB0_563
	s_setprio 1
	s_waitcnt lgkmcnt(0)
	v_mfma_f32_16x16x32_bf16 v[62:65], v[146:149], v[174:177], v[62:65]
	v_mfma_f32_16x16x32_bf16 v[58:61], v[154:157], v[174:177], v[58:61]
	v_mfma_f32_16x16x32_bf16 v[46:49], v[146:149], v[170:173], v[46:49]
	v_mfma_f32_16x16x32_bf16 v[42:45], v[154:157], v[170:173], v[42:45]
	v_mfma_f32_16x16x32_bf16 v[30:33], v[146:149], v[166:169], v[30:33]
	v_mfma_f32_16x16x32_bf16 v[26:29], v[154:157], v[166:169], v[26:29]
	v_mfma_f32_16x16x32_bf16 v[14:17], v[146:149], v[162:165], v[14:17]
	v_mfma_f32_16x16x32_bf16 v[10:13], v[154:157], v[162:165], v[10:13]
	v_mfma_f32_16x16x32_bf16 v[62:65], v[150:153], v[190:193], v[62:65]
	v_mfma_f32_16x16x32_bf16 v[58:61], v[158:161], v[190:193], v[58:61]
	v_mfma_f32_16x16x32_bf16 v[46:49], v[150:153], v[186:189], v[46:49]
	v_mfma_f32_16x16x32_bf16 v[42:45], v[158:161], v[186:189], v[42:45]
	v_mfma_f32_16x16x32_bf16 v[30:33], v[150:153], v[182:185], v[30:33]
	v_mfma_f32_16x16x32_bf16 v[26:29], v[158:161], v[182:185], v[26:29]
	v_mfma_f32_16x16x32_bf16 v[14:17], v[150:153], v[178:181], v[14:17]
	v_mfma_f32_16x16x32_bf16 v[10:13], v[158:161], v[178:181], v[10:13]
	s_setprio 0
	s_setprio 1
	v_mfma_f32_16x16x32_bf16 v[54:57], v[130:133], v[174:177], v[54:57]
	v_mfma_f32_16x16x32_bf16 v[50:53], v[138:141], v[174:177], v[50:53]
	v_mfma_f32_16x16x32_bf16 v[38:41], v[130:133], v[170:173], v[38:41]
	v_mfma_f32_16x16x32_bf16 v[34:37], v[138:141], v[170:173], v[34:37]
	v_mfma_f32_16x16x32_bf16 v[22:25], v[130:133], v[166:169], v[22:25]
	v_mfma_f32_16x16x32_bf16 v[18:21], v[138:141], v[166:169], v[18:21]
	v_mfma_f32_16x16x32_bf16 v[6:9], v[130:133], v[162:165], v[6:9]
	v_mfma_f32_16x16x32_bf16 v[2:5], v[138:141], v[162:165], v[2:5]
	v_mfma_f32_16x16x32_bf16 v[54:57], v[134:137], v[190:193], v[54:57]
	v_mfma_f32_16x16x32_bf16 v[50:53], v[142:145], v[190:193], v[50:53]
	v_mfma_f32_16x16x32_bf16 v[38:41], v[134:137], v[186:189], v[38:41]
	v_mfma_f32_16x16x32_bf16 v[34:37], v[142:145], v[186:189], v[34:37]
	v_mfma_f32_16x16x32_bf16 v[22:25], v[134:137], v[182:185], v[22:25]
	v_mfma_f32_16x16x32_bf16 v[18:21], v[142:145], v[182:185], v[18:21]
	v_mfma_f32_16x16x32_bf16 v[6:9], v[134:137], v[178:181], v[6:9]
	v_mfma_f32_16x16x32_bf16 v[2:5], v[142:145], v[178:181], v[2:5]
	s_setprio 0
.LBB0_563:
	s_and_b64 vcc, s[40:41], s[68:69]
	v_cndmask_b32_e64 v131, v215, 0, vcc
	v_cndmask_b32_e32 v130, v214, v198, vcc
	v_lshl_add_u64 v[234:235], s[62:63], 0, v[130:131]
	s_barrier
	s_mov_b32 m0, s8
	s_nop 0
	global_load_lds_dwordx4 v194, s[98:99]
	s_mov_b32 m0, s13
	s_nop 0
	global_load_lds_dwordx4 v196, s[98:99]
	v_add_u32_e32 v130, 0x18000, v226
	v_add_u32_e32 v142, 0x1c000, v226
	ds_read_b128 v[146:149], v130
	ds_read_b128 v[150:153], v130 offset:1024
	ds_read_b128 v[154:157], v130 offset:2048
	ds_read_b128 v[158:161], v130 offset:3072
	ds_read_b128 v[130:133], v142
	ds_read_b128 v[134:137], v142 offset:1024
	ds_read_b128 v[138:141], v142 offset:2048
	ds_read_b128 v[142:145], v142 offset:3072
	s_mov_b32 m0, s14
	v_lshl_add_u64 v[236:237], v[234:235], 0, v[194:195]
	s_waitcnt lgkmcnt(0)
	ds_read_b128 v[174:177], v229 offset:32768
	ds_read_b128 v[190:193], v229 offset:33792
	ds_read_b128 v[170:173], v229 offset:34816
	ds_read_b128 v[186:189], v229 offset:35840
	ds_read_b128 v[166:169], v229 offset:36864
	ds_read_b128 v[182:185], v229 offset:37888
	ds_read_b128 v[162:165], v229 offset:38912
	ds_read_b128 v[178:181], v229 offset:39936
	global_load_lds_dwordx4 v[236:237], off
	v_lshl_add_u64 v[234:235], v[234:235], 0, v[196:197]
	s_mov_b32 m0, s15
	s_nop 0
	global_load_lds_dwordx4 v[234:235], off
	s_waitcnt vmcnt(8)
	s_waitcnt lgkmcnt(0)
	s_barrier
	s_setprio 1
	s_waitcnt lgkmcnt(0)
	v_mfma_f32_16x16x32_bf16 v[126:129], v[146:149], v[174:177], v[126:129]
	v_mfma_f32_16x16x32_bf16 v[122:125], v[154:157], v[174:177], v[122:125]
	v_mfma_f32_16x16x32_bf16 v[110:113], v[146:149], v[170:173], v[110:113]
	v_mfma_f32_16x16x32_bf16 v[106:109], v[154:157], v[170:173], v[106:109]
	v_mfma_f32_16x16x32_bf16 v[94:97], v[146:149], v[166:169], v[94:97]
	v_mfma_f32_16x16x32_bf16 v[90:93], v[154:157], v[166:169], v[90:93]
	v_mfma_f32_16x16x32_bf16 v[78:81], v[146:149], v[162:165], v[78:81]
	v_mfma_f32_16x16x32_bf16 v[74:77], v[154:157], v[162:165], v[74:77]
	v_mfma_f32_16x16x32_bf16 v[126:129], v[150:153], v[190:193], v[126:129]
	v_mfma_f32_16x16x32_bf16 v[122:125], v[158:161], v[190:193], v[122:125]
	v_mfma_f32_16x16x32_bf16 v[110:113], v[150:153], v[186:189], v[110:113]
	v_mfma_f32_16x16x32_bf16 v[106:109], v[158:161], v[186:189], v[106:109]
	v_mfma_f32_16x16x32_bf16 v[94:97], v[150:153], v[182:185], v[94:97]
	v_mfma_f32_16x16x32_bf16 v[90:93], v[158:161], v[182:185], v[90:93]
	v_mfma_f32_16x16x32_bf16 v[78:81], v[150:153], v[178:181], v[78:81]
	v_mfma_f32_16x16x32_bf16 v[74:77], v[158:161], v[178:181], v[74:77]
	s_setprio 0
	s_setprio 1
	s_add_u32 s68, s60, 0x40000
	s_addc_u32 s69, s61, 0
	s_add_u32 s62, s62, 0x220000
	s_addc_u32 s63, s63, 0
	v_mfma_f32_16x16x32_bf16 v[118:121], v[130:133], v[174:177], v[118:121]
	v_mfma_f32_16x16x32_bf16 v[114:117], v[138:141], v[174:177], v[114:117]
	v_mfma_f32_16x16x32_bf16 v[102:105], v[130:133], v[170:173], v[102:105]
	v_mfma_f32_16x16x32_bf16 v[98:101], v[138:141], v[170:173], v[98:101]
	v_mfma_f32_16x16x32_bf16 v[86:89], v[130:133], v[166:169], v[86:89]
	v_mfma_f32_16x16x32_bf16 v[82:85], v[138:141], v[166:169], v[82:85]
	v_mfma_f32_16x16x32_bf16 v[70:73], v[130:133], v[162:165], v[70:73]
	v_mfma_f32_16x16x32_bf16 v[66:69], v[138:141], v[162:165], v[66:69]
	v_mfma_f32_16x16x32_bf16 v[118:121], v[134:137], v[190:193], v[118:121]
	v_mfma_f32_16x16x32_bf16 v[114:117], v[142:145], v[190:193], v[114:117]
	v_mfma_f32_16x16x32_bf16 v[102:105], v[134:137], v[186:189], v[102:105]
	v_mfma_f32_16x16x32_bf16 v[98:101], v[142:145], v[186:189], v[98:101]
	v_mfma_f32_16x16x32_bf16 v[86:89], v[134:137], v[182:185], v[86:89]
	v_mfma_f32_16x16x32_bf16 v[82:85], v[142:145], v[182:185], v[82:85]
	v_mfma_f32_16x16x32_bf16 v[70:73], v[134:137], v[178:181], v[70:73]
	v_mfma_f32_16x16x32_bf16 v[66:69], v[142:145], v[178:181], v[66:69]
	s_setprio 0
	s_barrier
	s_and_b64 vcc, exec, s[42:43]
	s_cbranch_vccnz .LBB0_565
	ds_read_b128 v[174:177], v229 offset:49152
	ds_read_b128 v[190:193], v229 offset:50176
	ds_read_b128 v[170:173], v229 offset:51200
	ds_read_b128 v[186:189], v229 offset:52224
	ds_read_b128 v[166:169], v229 offset:53248
	ds_read_b128 v[182:185], v229 offset:54272
	ds_read_b128 v[162:165], v229 offset:55296
	ds_read_b128 v[178:181], v229 offset:56320
.LBB0_565:
	s_mov_b32 m0, s17
	s_add_u32 s60, s60, 0x44000
	global_load_lds_dwordx4 v194, s[68:69]
	s_mov_b32 m0, s54
	s_addc_u32 s61, s61, 0
	global_load_lds_dwordx4 v196, s[68:69]
	s_mov_b32 m0, s70
	s_and_b64 vcc, exec, s[42:43]
	global_load_lds_dwordx4 v194, s[60:61]
	s_mov_b32 m0, s71
	s_nop 0
	global_load_lds_dwordx4 v196, s[60:61]
	s_mov_b64 s[100:101], s[62:63]
	s_waitcnt vmcnt(6)
	s_waitcnt lgkmcnt(0)
	s_barrier
	s_cbranch_vccnz .LBB0_558
	s_setprio 1
	s_waitcnt lgkmcnt(0)
	v_mfma_f32_16x16x32_bf16 v[62:65], v[146:149], v[174:177], v[62:65]
	v_mfma_f32_16x16x32_bf16 v[58:61], v[154:157], v[174:177], v[58:61]
	v_mfma_f32_16x16x32_bf16 v[46:49], v[146:149], v[170:173], v[46:49]
	v_mfma_f32_16x16x32_bf16 v[42:45], v[154:157], v[170:173], v[42:45]
	v_mfma_f32_16x16x32_bf16 v[30:33], v[146:149], v[166:169], v[30:33]
	v_mfma_f32_16x16x32_bf16 v[26:29], v[154:157], v[166:169], v[26:29]
	v_mfma_f32_16x16x32_bf16 v[14:17], v[146:149], v[162:165], v[14:17]
	v_mfma_f32_16x16x32_bf16 v[10:13], v[154:157], v[162:165], v[10:13]
	v_mfma_f32_16x16x32_bf16 v[62:65], v[150:153], v[190:193], v[62:65]
	v_mfma_f32_16x16x32_bf16 v[58:61], v[158:161], v[190:193], v[58:61]
	v_mfma_f32_16x16x32_bf16 v[46:49], v[150:153], v[186:189], v[46:49]
	v_mfma_f32_16x16x32_bf16 v[42:45], v[158:161], v[186:189], v[42:45]
	v_mfma_f32_16x16x32_bf16 v[30:33], v[150:153], v[182:185], v[30:33]
	v_mfma_f32_16x16x32_bf16 v[26:29], v[158:161], v[182:185], v[26:29]
	v_mfma_f32_16x16x32_bf16 v[14:17], v[150:153], v[178:181], v[14:17]
	v_mfma_f32_16x16x32_bf16 v[10:13], v[158:161], v[178:181], v[10:13]
	s_setprio 0
	s_setprio 1
	v_mfma_f32_16x16x32_bf16 v[54:57], v[130:133], v[174:177], v[54:57]
	v_mfma_f32_16x16x32_bf16 v[50:53], v[138:141], v[174:177], v[50:53]
	v_mfma_f32_16x16x32_bf16 v[38:41], v[130:133], v[170:173], v[38:41]
	v_mfma_f32_16x16x32_bf16 v[34:37], v[138:141], v[170:173], v[34:37]
	v_mfma_f32_16x16x32_bf16 v[22:25], v[130:133], v[166:169], v[22:25]
	v_mfma_f32_16x16x32_bf16 v[18:21], v[138:141], v[166:169], v[18:21]
	v_mfma_f32_16x16x32_bf16 v[6:9], v[130:133], v[162:165], v[6:9]
	v_mfma_f32_16x16x32_bf16 v[2:5], v[138:141], v[162:165], v[2:5]
	v_mfma_f32_16x16x32_bf16 v[54:57], v[134:137], v[190:193], v[54:57]
	v_mfma_f32_16x16x32_bf16 v[50:53], v[142:145], v[190:193], v[50:53]
	v_mfma_f32_16x16x32_bf16 v[38:41], v[134:137], v[186:189], v[38:41]
	v_mfma_f32_16x16x32_bf16 v[34:37], v[142:145], v[186:189], v[34:37]
	v_mfma_f32_16x16x32_bf16 v[22:25], v[134:137], v[182:185], v[22:25]
	v_mfma_f32_16x16x32_bf16 v[18:21], v[142:145], v[182:185], v[18:21]
	v_mfma_f32_16x16x32_bf16 v[6:9], v[134:137], v[178:181], v[6:9]
	v_mfma_f32_16x16x32_bf16 v[2:5], v[142:145], v[178:181], v[2:5]
	s_setprio 0
	s_branch .LBB0_558

.LBB0_761:
	s_mov_b32 m0, s14
	s_nop 0
	global_load_lds_dwordx4 v194, s[100:101]
	s_mov_b32 m0, s15
	s_nop 0
	global_load_lds_dwordx4 v196, s[100:101]
	ds_read_b128 v[130:133], v237
	ds_read_b128 v[134:137], v237 offset:1024
	ds_read_b128 v[138:141], v237 offset:2048
	ds_read_b128 v[142:145], v237 offset:3072
	ds_read_b128 v[146:149], v238
	ds_read_b128 v[150:153], v238 offset:1024
	ds_read_b128 v[154:157], v238 offset:2048
	ds_read_b128 v[158:161], v238 offset:3072
	v_lshl_add_u64 v[208:209], s[0:1], 0, v[202:203]
	s_add_i32 m0, s9, 0xc000
	ds_read_b128 v[162:165], v239
	ds_read_b128 v[166:169], v239 offset:1024
	ds_read_b128 v[170:173], v239 offset:2048
	ds_read_b128 v[174:177], v239 offset:3072
	ds_read_b128 v[178:181], v239 offset:4096
	ds_read_b128 v[182:185], v239 offset:5120
	ds_read_b128 v[186:189], v239 offset:6144
	ds_read_b128 v[190:193], v239 offset:7168
	global_load_lds_dwordx4 v[208:209], off
	v_lshl_add_u64 v[208:209], s[0:1], 0, v[200:201]
	s_add_i32 m0, s9, 0xe000
	s_nop 0
	global_load_lds_dwordx4 v[208:209], off
	s_waitcnt vmcnt(8)
	s_waitcnt lgkmcnt(0)
	s_barrier
	s_setprio 1
	s_waitcnt lgkmcnt(0)
	v_mfma_f32_16x16x32_bf16 v[126:129], v[130:133], v[162:165], v[126:129]
	v_mfma_f32_16x16x32_bf16 v[122:125], v[138:141], v[162:165], v[122:125]
	s_add_u32 s48, s0, 0x21c000
	s_addc_u32 s49, s1, 0
	s_cmp_eq_u32 s67, 28
	s_cselect_b32 s42, s55, s62
	s_cselect_b32 s43, s29, s63
	s_cselect_b32 s52, s45, s48
	s_cselect_b32 s53, s31, s49
	s_add_u32 s50, s42, 0xe0000
	s_addc_u32 s51, s43, 0
	s_add_u32 s48, s52, 0x220000
	s_addc_u32 s49, s53, 0
	v_mfma_f32_16x16x32_bf16 v[118:121], v[130:133], v[170:173], v[118:121]
	v_mfma_f32_16x16x32_bf16 v[114:117], v[138:141], v[170:173], v[114:117]
	v_mfma_f32_16x16x32_bf16 v[110:113], v[130:133], v[178:181], v[110:113]
	v_mfma_f32_16x16x32_bf16 v[106:109], v[138:141], v[178:181], v[106:109]
	v_mfma_f32_16x16x32_bf16 v[102:105], v[130:133], v[186:189], v[102:105]
	v_mfma_f32_16x16x32_bf16 v[98:101], v[138:141], v[186:189], v[98:101]
	v_mfma_f32_16x16x32_bf16 v[126:129], v[134:137], v[166:169], v[126:129]
	v_mfma_f32_16x16x32_bf16 v[122:125], v[142:145], v[166:169], v[122:125]
	v_mfma_f32_16x16x32_bf16 v[118:121], v[134:137], v[174:177], v[118:121]
	v_mfma_f32_16x16x32_bf16 v[114:117], v[142:145], v[174:177], v[114:117]
	v_mfma_f32_16x16x32_bf16 v[110:113], v[134:137], v[182:185], v[110:113]
	v_mfma_f32_16x16x32_bf16 v[106:109], v[142:145], v[182:185], v[106:109]
	v_mfma_f32_16x16x32_bf16 v[102:105], v[134:137], v[190:193], v[102:105]
	v_mfma_f32_16x16x32_bf16 v[98:101], v[142:145], v[190:193], v[98:101]
	s_setprio 0
	s_setprio 1
	v_mfma_f32_16x16x32_bf16 v[62:65], v[146:149], v[162:165], v[62:65]
	s_add_u32 s60, s52, 0x4000
	s_addc_u32 s61, s53, 0
	v_mfma_f32_16x16x32_bf16 v[58:61], v[154:157], v[162:165], v[58:61]
	v_mfma_f32_16x16x32_bf16 v[54:57], v[146:149], v[170:173], v[54:57]
	v_mfma_f32_16x16x32_bf16 v[50:53], v[154:157], v[170:173], v[50:53]
	v_mfma_f32_16x16x32_bf16 v[46:49], v[146:149], v[178:181], v[46:49]
	v_mfma_f32_16x16x32_bf16 v[42:45], v[154:157], v[178:181], v[42:45]
	v_mfma_f32_16x16x32_bf16 v[38:41], v[146:149], v[186:189], v[38:41]
	v_mfma_f32_16x16x32_bf16 v[34:37], v[154:157], v[186:189], v[34:37]
	v_mfma_f32_16x16x32_bf16 v[62:65], v[150:153], v[166:169], v[62:65]
	v_mfma_f32_16x16x32_bf16 v[58:61], v[158:161], v[166:169], v[58:61]
	v_mfma_f32_16x16x32_bf16 v[54:57], v[150:153], v[174:177], v[54:57]
	v_mfma_f32_16x16x32_bf16 v[50:53], v[158:161], v[174:177], v[50:53]
	v_mfma_f32_16x16x32_bf16 v[46:49], v[150:153], v[182:185], v[46:49]
	v_mfma_f32_16x16x32_bf16 v[42:45], v[158:161], v[182:185], v[42:45]
	v_mfma_f32_16x16x32_bf16 v[38:41], v[150:153], v[190:193], v[38:41]
	v_mfma_f32_16x16x32_bf16 v[34:37], v[158:161], v[190:193], v[34:37]
	s_setprio 0
	s_barrier
	s_add_i32 s68, s16, s8
	s_mov_b32 m0, s68
	ds_read_b128 v[162:165], v239 offset:16384
	ds_read_b128 v[166:169], v239 offset:17408
	ds_read_b128 v[170:173], v239 offset:18432
	ds_read_b128 v[174:177], v239 offset:19456
	ds_read_b128 v[178:181], v239 offset:20480
	ds_read_b128 v[182:185], v239 offset:21504
	ds_read_b128 v[186:189], v239 offset:22528
	ds_read_b128 v[190:193], v239 offset:23552
	global_load_lds_dwordx4 v194, s[42:43]
	s_add_i32 m0, s68, 0x2000
	s_add_u32 s68, s42, 0x4000
	s_addc_u32 s69, s43, 0
	s_add_i32 s70, s17, s8
	global_load_lds_dwordx4 v196, s[42:43]
	s_mov_b32 m0, s70
	s_nop 0
	global_load_lds_dwordx4 v194, s[68:69]
	s_add_i32 m0, s70, 0x2000
	s_nop 0
	global_load_lds_dwordx4 v196, s[68:69]
	s_mov_b64 s[98:99], s[52:53]
	s_waitcnt vmcnt(6)
	s_waitcnt lgkmcnt(0)
	s_barrier
	s_setprio 1
	s_waitcnt lgkmcnt(0)
	v_mfma_f32_16x16x32_bf16 v[94:97], v[130:133], v[162:165], v[94:97]
	v_mfma_f32_16x16x32_bf16 v[90:93], v[138:141], v[162:165], v[90:93]
	v_mfma_f32_16x16x32_bf16 v[86:89], v[130:133], v[170:173], v[86:89]
	v_mfma_f32_16x16x32_bf16 v[82:85], v[138:141], v[170:173], v[82:85]
	v_mfma_f32_16x16x32_bf16 v[78:81], v[130:133], v[178:181], v[78:81]
	v_mfma_f32_16x16x32_bf16 v[74:77], v[138:141], v[178:181], v[74:77]
	v_mfma_f32_16x16x32_bf16 v[70:73], v[130:133], v[186:189], v[70:73]
	v_mfma_f32_16x16x32_bf16 v[66:69], v[138:141], v[186:189], v[66:69]
	v_mfma_f32_16x16x32_bf16 v[94:97], v[134:137], v[166:169], v[94:97]
	v_mfma_f32_16x16x32_bf16 v[90:93], v[142:145], v[166:169], v[90:93]
	v_mfma_f32_16x16x32_bf16 v[86:89], v[134:137], v[174:177], v[86:89]
	v_mfma_f32_16x16x32_bf16 v[82:85], v[142:145], v[174:177], v[82:85]
	v_mfma_f32_16x16x32_bf16 v[78:81], v[134:137], v[182:185], v[78:81]
	v_mfma_f32_16x16x32_bf16 v[74:77], v[142:145], v[182:185], v[74:77]
	v_mfma_f32_16x16x32_bf16 v[70:73], v[134:137], v[190:193], v[70:73]
	v_mfma_f32_16x16x32_bf16 v[66:69], v[142:145], v[190:193], v[66:69]
	s_setprio 0
	s_setprio 1
	v_mfma_f32_16x16x32_bf16 v[30:33], v[146:149], v[162:165], v[30:33]
	v_mfma_f32_16x16x32_bf16 v[26:29], v[154:157], v[162:165], v[26:29]
	v_mfma_f32_16x16x32_bf16 v[22:25], v[146:149], v[170:173], v[22:25]
	v_mfma_f32_16x16x32_bf16 v[18:21], v[154:157], v[170:173], v[18:21]
	v_mfma_f32_16x16x32_bf16 v[14:17], v[146:149], v[178:181], v[14:17]
	v_mfma_f32_16x16x32_bf16 v[10:13], v[154:157], v[178:181], v[10:13]
	v_mfma_f32_16x16x32_bf16 v[6:9], v[146:149], v[186:189], v[6:9]
	v_mfma_f32_16x16x32_bf16 v[2:5], v[154:157], v[186:189], v[2:5]
	v_mfma_f32_16x16x32_bf16 v[30:33], v[150:153], v[166:169], v[30:33]
	v_mfma_f32_16x16x32_bf16 v[26:29], v[158:161], v[166:169], v[26:29]
	v_mfma_f32_16x16x32_bf16 v[22:25], v[150:153], v[174:177], v[22:25]
	v_mfma_f32_16x16x32_bf16 v[18:21], v[158:161], v[174:177], v[18:21]
	v_mfma_f32_16x16x32_bf16 v[14:17], v[150:153], v[182:185], v[14:17]
	v_mfma_f32_16x16x32_bf16 v[10:13], v[158:161], v[182:185], v[10:13]
	v_mfma_f32_16x16x32_bf16 v[6:9], v[150:153], v[190:193], v[6:9]
	v_mfma_f32_16x16x32_bf16 v[2:5], v[158:161], v[190:193], v[2:5]
	s_setprio 0
	s_barrier
	s_mov_b32 m0, s9
	s_nop 0
	global_load_lds_dwordx4 v194, s[98:99]
	s_mov_b32 m0, s10
	s_nop 0
	global_load_lds_dwordx4 v196, s[98:99]
	s_add_i32 s52, 0, 0x18000
	s_add_i32 s53, 0, 0x1c000
	v_add_u32_e32 v142, s52, v228
	v_add_u32_e32 v158, s53, v228
	ds_read_b128 v[130:133], v142
	ds_read_b128 v[134:137], v142 offset:1024
	ds_read_b128 v[138:141], v142 offset:2048
	ds_read_b128 v[142:145], v142 offset:3072
	ds_read_b128 v[146:149], v158
	ds_read_b128 v[150:153], v158 offset:1024
	ds_read_b128 v[154:157], v158 offset:2048
	ds_read_b128 v[158:161], v158 offset:3072
	s_mov_b32 m0, s11
	ds_read_b128 v[162:165], v239 offset:32768
	ds_read_b128 v[166:169], v239 offset:33792
	ds_read_b128 v[170:173], v239 offset:34816
	ds_read_b128 v[174:177], v239 offset:35840
	ds_read_b128 v[178:181], v239 offset:36864
	ds_read_b128 v[182:185], v239 offset:37888
	ds_read_b128 v[186:189], v239 offset:38912
	ds_read_b128 v[190:193], v239 offset:39936
	global_load_lds_dwordx4 v194, s[60:61]
	s_mov_b32 m0, s12
	s_nop 0
	global_load_lds_dwordx4 v196, s[60:61]
	s_waitcnt vmcnt(8)
	s_waitcnt lgkmcnt(0)
	s_barrier
	s_setprio 1
	s_waitcnt lgkmcnt(0)
	v_mfma_f32_16x16x32_bf16 v[126:129], v[130:133], v[162:165], v[126:129]
	v_mfma_f32_16x16x32_bf16 v[122:125], v[138:141], v[162:165], v[122:125]
	v_mfma_f32_16x16x32_bf16 v[118:121], v[130:133], v[170:173], v[118:121]
	v_mfma_f32_16x16x32_bf16 v[114:117], v[138:141], v[170:173], v[114:117]
	v_mfma_f32_16x16x32_bf16 v[110:113], v[130:133], v[178:181], v[110:113]
	v_mfma_f32_16x16x32_bf16 v[106:109], v[138:141], v[178:181], v[106:109]
	v_mfma_f32_16x16x32_bf16 v[102:105], v[130:133], v[186:189], v[102:105]
	v_mfma_f32_16x16x32_bf16 v[98:101], v[138:141], v[186:189], v[98:101]
	v_mfma_f32_16x16x32_bf16 v[126:129], v[134:137], v[166:169], v[126:129]
	v_mfma_f32_16x16x32_bf16 v[122:125], v[142:145], v[166:169], v[122:125]
	v_mfma_f32_16x16x32_bf16 v[118:121], v[134:137], v[174:177], v[118:121]
	v_mfma_f32_16x16x32_bf16 v[114:117], v[142:145], v[174:177], v[114:117]
	v_mfma_f32_16x16x32_bf16 v[110:113], v[134:137], v[182:185], v[110:113]
	v_mfma_f32_16x16x32_bf16 v[106:109], v[142:145], v[182:185], v[106:109]
	v_mfma_f32_16x16x32_bf16 v[102:105], v[134:137], v[190:193], v[102:105]
	v_mfma_f32_16x16x32_bf16 v[98:101], v[142:145], v[190:193], v[98:101]
	s_setprio 0
	s_setprio 1
	s_add_i32 s52, s52, s8
	v_mfma_f32_16x16x32_bf16 v[62:65], v[146:149], v[162:165], v[62:65]
	v_mfma_f32_16x16x32_bf16 v[58:61], v[154:157], v[162:165], v[58:61]
	v_mfma_f32_16x16x32_bf16 v[54:57], v[146:149], v[170:173], v[54:57]
	v_mfma_f32_16x16x32_bf16 v[50:53], v[154:157], v[170:173], v[50:53]
	v_mfma_f32_16x16x32_bf16 v[46:49], v[146:149], v[178:181], v[46:49]
	v_mfma_f32_16x16x32_bf16 v[42:45], v[154:157], v[178:181], v[42:45]
	v_mfma_f32_16x16x32_bf16 v[38:41], v[146:149], v[186:189], v[38:41]
	v_mfma_f32_16x16x32_bf16 v[34:37], v[154:157], v[186:189], v[34:37]
	v_mfma_f32_16x16x32_bf16 v[62:65], v[150:153], v[166:169], v[62:65]
	v_mfma_f32_16x16x32_bf16 v[58:61], v[158:161], v[166:169], v[58:61]
	v_mfma_f32_16x16x32_bf16 v[54:57], v[150:153], v[174:177], v[54:57]
	v_mfma_f32_16x16x32_bf16 v[50:53], v[158:161], v[174:177], v[50:53]
	v_mfma_f32_16x16x32_bf16 v[46:49], v[150:153], v[182:185], v[46:49]
	v_mfma_f32_16x16x32_bf16 v[42:45], v[158:161], v[182:185], v[42:45]
	v_mfma_f32_16x16x32_bf16 v[38:41], v[150:153], v[190:193], v[38:41]
	v_mfma_f32_16x16x32_bf16 v[34:37], v[158:161], v[190:193], v[34:37]
	s_setprio 0
	s_barrier
	s_mov_b32 m0, s52
	ds_read_b128 v[162:165], v239 offset:49152
	ds_read_b128 v[166:169], v239 offset:50176
	ds_read_b128 v[170:173], v239 offset:51200
	ds_read_b128 v[174:177], v239 offset:52224
	ds_read_b128 v[178:181], v239 offset:53248
	ds_read_b128 v[182:185], v239 offset:54272
	ds_read_b128 v[186:189], v239 offset:55296
	ds_read_b128 v[190:193], v239 offset:56320
	global_load_lds_dwordx4 v194, s[50:51]
	s_add_i32 m0, s52, 0x2000
	s_add_u32 s42, s42, 0xe4000
	v_lshl_add_u64 v[208:209], s[50:51], 0, v[196:197]
	s_addc_u32 s43, s43, 0
	s_add_i32 s50, s53, s8
	global_load_lds_dwordx4 v[208:209], off
	s_mov_b32 m0, s50
	s_nop 0
	global_load_lds_dwordx4 v194, s[42:43]
	s_add_i32 m0, s50, 0x2000
	s_nop 0
	global_load_lds_dwordx4 v196, s[42:43]
	s_mov_b64 s[100:101], s[48:49]
	s_waitcnt vmcnt(6)
	s_waitcnt lgkmcnt(0)
	s_barrier
	s_setprio 1
	s_waitcnt lgkmcnt(0)
	v_mfma_f32_16x16x32_bf16 v[94:97], v[130:133], v[162:165], v[94:97]
	v_mfma_f32_16x16x32_bf16 v[90:93], v[138:141], v[162:165], v[90:93]
	v_mfma_f32_16x16x32_bf16 v[86:89], v[130:133], v[170:173], v[86:89]
	v_mfma_f32_16x16x32_bf16 v[82:85], v[138:141], v[170:173], v[82:85]
	v_mfma_f32_16x16x32_bf16 v[78:81], v[130:133], v[178:181], v[78:81]
	v_mfma_f32_16x16x32_bf16 v[74:77], v[138:141], v[178:181], v[74:77]
	v_mfma_f32_16x16x32_bf16 v[70:73], v[130:133], v[186:189], v[70:73]
	v_mfma_f32_16x16x32_bf16 v[66:69], v[138:141], v[186:189], v[66:69]
	v_mfma_f32_16x16x32_bf16 v[94:97], v[134:137], v[166:169], v[94:97]
	v_mfma_f32_16x16x32_bf16 v[90:93], v[142:145], v[166:169], v[90:93]
	v_mfma_f32_16x16x32_bf16 v[86:89], v[134:137], v[174:177], v[86:89]
	v_mfma_f32_16x16x32_bf16 v[82:85], v[142:145], v[174:177], v[82:85]
	v_mfma_f32_16x16x32_bf16 v[78:81], v[134:137], v[182:185], v[78:81]
	v_mfma_f32_16x16x32_bf16 v[74:77], v[142:145], v[182:185], v[74:77]
	v_mfma_f32_16x16x32_bf16 v[70:73], v[134:137], v[190:193], v[70:73]
	v_mfma_f32_16x16x32_bf16 v[66:69], v[142:145], v[190:193], v[66:69]
	s_setprio 0
	s_setprio 1
	v_mfma_f32_16x16x32_bf16 v[30:33], v[146:149], v[162:165], v[30:33]
	v_mfma_f32_16x16x32_bf16 v[26:29], v[154:157], v[162:165], v[26:29]
	v_mfma_f32_16x16x32_bf16 v[22:25], v[146:149], v[170:173], v[22:25]
	v_mfma_f32_16x16x32_bf16 v[18:21], v[154:157], v[170:173], v[18:21]
	v_mfma_f32_16x16x32_bf16 v[14:17], v[146:149], v[178:181], v[14:17]
	v_mfma_f32_16x16x32_bf16 v[10:13], v[154:157], v[178:181], v[10:13]
	v_mfma_f32_16x16x32_bf16 v[6:9], v[146:149], v[186:189], v[6:9]
	v_mfma_f32_16x16x32_bf16 v[2:5], v[154:157], v[186:189], v[2:5]
	v_mfma_f32_16x16x32_bf16 v[30:33], v[150:153], v[166:169], v[30:33]
	v_mfma_f32_16x16x32_bf16 v[26:29], v[158:161], v[166:169], v[26:29]
	v_mfma_f32_16x16x32_bf16 v[22:25], v[150:153], v[174:177], v[22:25]
	v_mfma_f32_16x16x32_bf16 v[18:21], v[158:161], v[174:177], v[18:21]
	v_mfma_f32_16x16x32_bf16 v[14:17], v[150:153], v[182:185], v[14:17]
	v_mfma_f32_16x16x32_bf16 v[10:13], v[158:161], v[182:185], v[10:13]
	v_mfma_f32_16x16x32_bf16 v[6:9], v[150:153], v[190:193], v[6:9]
	v_mfma_f32_16x16x32_bf16 v[2:5], v[158:161], v[190:193], v[2:5]
	s_setprio 0
	s_barrier
	s_add_i32 s67, s67, 2
	s_add_u32 s62, s62, 0x1c0000
	s_addc_u32 s63, s63, 0
	s_add_u32 s0, s0, 0x440000
	s_addc_u32 s1, s1, 0
	s_cmp_gt_u32 s67, 29
	s_cbranch_scc0 .LBB0_761
	s_and_b64 vcc, exec, s[26:27]
	s_cbranch_vccz .LBB0_764
	s_barrier

.LBB0_903:
	s_mov_b32 m0, s23
	s_nop 0
	global_load_lds_dwordx4 v194, s[100:101]
	s_mov_b32 m0, s31
	s_nop 0
	global_load_lds_dwordx4 v196, s[100:101]
	ds_read_b128 v[146:149], v225
	ds_read_b128 v[150:153], v225 offset:1024
	ds_read_b128 v[154:157], v225 offset:2048
	ds_read_b128 v[158:161], v225 offset:3072
	ds_read_b128 v[130:133], v227
	ds_read_b128 v[134:137], v227 offset:1024
	ds_read_b128 v[138:141], v227 offset:2048
	ds_read_b128 v[142:145], v227 offset:3072
	v_lshl_add_u64 v[234:235], v[210:211], 0, s[62:63]
	s_add_i32 m0, s8, 0xc000
	s_waitcnt lgkmcnt(0)
	ds_read_b128 v[174:177], v228
	ds_read_b128 v[190:193], v228 offset:1024
	ds_read_b128 v[170:173], v228 offset:2048
	ds_read_b128 v[186:189], v228 offset:3072
	ds_read_b128 v[166:169], v228 offset:4096
	ds_read_b128 v[182:185], v228 offset:5120
	ds_read_b128 v[162:165], v228 offset:6144
	ds_read_b128 v[178:181], v228 offset:7168
	global_load_lds_dwordx4 v[234:235], off
	v_lshl_add_u64 v[234:235], v[212:213], 0, s[62:63]
	s_add_i32 m0, s8, 0xe000
	s_nop 0
	global_load_lds_dwordx4 v[234:235], off
	s_waitcnt vmcnt(8)
	s_waitcnt lgkmcnt(0)
	s_barrier
	s_setprio 1
	s_waitcnt lgkmcnt(0)
	v_mfma_f32_16x16x32_bf16 v[126:129], v[146:149], v[174:177], v[126:129]
	v_mfma_f32_16x16x32_bf16 v[122:125], v[154:157], v[174:177], v[122:125]
	v_mfma_f32_16x16x32_bf16 v[118:121], v[146:149], v[170:173], v[118:121]
	v_mfma_f32_16x16x32_bf16 v[114:117], v[154:157], v[170:173], v[114:117]
	v_mfma_f32_16x16x32_bf16 v[110:113], v[146:149], v[166:169], v[110:113]
	v_mfma_f32_16x16x32_bf16 v[106:109], v[154:157], v[166:169], v[106:109]
	v_mfma_f32_16x16x32_bf16 v[102:105], v[146:149], v[162:165], v[102:105]
	v_mfma_f32_16x16x32_bf16 v[98:101], v[154:157], v[162:165], v[98:101]
	v_mfma_f32_16x16x32_bf16 v[126:129], v[150:153], v[190:193], v[126:129]
	v_mfma_f32_16x16x32_bf16 v[122:125], v[158:161], v[190:193], v[122:125]
	v_mfma_f32_16x16x32_bf16 v[118:121], v[150:153], v[186:189], v[118:121]
	v_mfma_f32_16x16x32_bf16 v[114:117], v[158:161], v[186:189], v[114:117]
	v_mfma_f32_16x16x32_bf16 v[110:113], v[150:153], v[182:185], v[110:113]
	v_mfma_f32_16x16x32_bf16 v[106:109], v[158:161], v[182:185], v[106:109]
	v_mfma_f32_16x16x32_bf16 v[102:105], v[150:153], v[178:181], v[102:105]
	v_mfma_f32_16x16x32_bf16 v[98:101], v[158:161], v[178:181], v[98:101]
	s_setprio 0
	s_setprio 1
	s_add_u32 s68, s0, s62
	s_addc_u32 s69, s1, s63
	s_add_u32 s70, s68, 0x440000
	s_addc_u32 s71, s69, 0
	s_cmp_eq_u32 s62, 0x3fc0000
	s_cselect_b64 s[72:73], -1, 0
	s_and_b64 s[68:69], s[72:73], exec
	s_cselect_b32 s69, s37, s77
	s_cselect_b32 s68, s75, s76
	s_cselect_b32 s71, s35, s71
	s_cselect_b32 s70, s74, s70
	v_mfma_f32_16x16x32_bf16 v[94:97], v[130:133], v[174:177], v[94:97]
	v_mfma_f32_16x16x32_bf16 v[90:93], v[138:141], v[174:177], v[90:93]
	v_mfma_f32_16x16x32_bf16 v[86:89], v[130:133], v[170:173], v[86:89]
	v_mfma_f32_16x16x32_bf16 v[82:85], v[138:141], v[170:173], v[82:85]
	v_mfma_f32_16x16x32_bf16 v[78:81], v[130:133], v[166:169], v[78:81]
	v_mfma_f32_16x16x32_bf16 v[74:77], v[138:141], v[166:169], v[74:77]
	v_mfma_f32_16x16x32_bf16 v[70:73], v[130:133], v[162:165], v[70:73]
	v_mfma_f32_16x16x32_bf16 v[66:69], v[138:141], v[162:165], v[66:69]
	v_mfma_f32_16x16x32_bf16 v[94:97], v[134:137], v[190:193], v[94:97]
	v_mfma_f32_16x16x32_bf16 v[90:93], v[142:145], v[190:193], v[90:93]
	v_mfma_f32_16x16x32_bf16 v[86:89], v[134:137], v[186:189], v[86:89]
	v_mfma_f32_16x16x32_bf16 v[82:85], v[142:145], v[186:189], v[82:85]
	v_mfma_f32_16x16x32_bf16 v[78:81], v[134:137], v[182:185], v[78:81]
	v_mfma_f32_16x16x32_bf16 v[74:77], v[142:145], v[182:185], v[74:77]
	v_mfma_f32_16x16x32_bf16 v[70:73], v[134:137], v[178:181], v[70:73]
	v_mfma_f32_16x16x32_bf16 v[66:69], v[142:145], v[178:181], v[66:69]
	s_setprio 0
	s_barrier
	v_cmp_ne_u32_e64 s[42:43], 1, v233
	s_andn2_b64 vcc, exec, s[44:45]
	s_cbranch_vccnz .LBB0_905
	ds_read_b128 v[174:177], v228 offset:16384
	ds_read_b128 v[190:193], v228 offset:17408
	ds_read_b128 v[170:173], v228 offset:18432
	ds_read_b128 v[186:189], v228 offset:19456
	ds_read_b128 v[166:169], v228 offset:20480
	ds_read_b128 v[182:185], v228 offset:21504
	ds_read_b128 v[162:165], v228 offset:22528
	ds_read_b128 v[178:181], v228 offset:23552
.LBB0_905:
	s_mov_b32 m0, s9
	s_add_u32 s80, s68, 0x4000
	global_load_lds_dwordx4 v194, s[68:69]
	s_mov_b32 m0, s10
	s_addc_u32 s81, s69, 0
	global_load_lds_dwordx4 v196, s[68:69]
	s_mov_b32 m0, s11
	s_and_b64 vcc, exec, s[42:43]
	global_load_lds_dwordx4 v194, s[80:81]
	s_mov_b32 m0, s12
	s_nop 0
	global_load_lds_dwordx4 v196, s[80:81]
	s_mov_b64 s[98:99], s[70:71]
	s_waitcnt vmcnt(6)
	s_waitcnt lgkmcnt(0)
	s_barrier
	s_cbranch_vccnz .LBB0_907
	s_setprio 1
	s_waitcnt lgkmcnt(0)
	v_mfma_f32_16x16x32_bf16 v[62:65], v[146:149], v[174:177], v[62:65]
	v_mfma_f32_16x16x32_bf16 v[58:61], v[154:157], v[174:177], v[58:61]
	v_mfma_f32_16x16x32_bf16 v[54:57], v[146:149], v[170:173], v[54:57]
	v_mfma_f32_16x16x32_bf16 v[50:53], v[154:157], v[170:173], v[50:53]
	v_mfma_f32_16x16x32_bf16 v[46:49], v[146:149], v[166:169], v[46:49]
	v_mfma_f32_16x16x32_bf16 v[42:45], v[154:157], v[166:169], v[42:45]
	v_mfma_f32_16x16x32_bf16 v[38:41], v[146:149], v[162:165], v[38:41]
	v_mfma_f32_16x16x32_bf16 v[34:37], v[154:157], v[162:165], v[34:37]
	v_mfma_f32_16x16x32_bf16 v[62:65], v[150:153], v[190:193], v[62:65]
	v_mfma_f32_16x16x32_bf16 v[58:61], v[158:161], v[190:193], v[58:61]
	v_mfma_f32_16x16x32_bf16 v[54:57], v[150:153], v[186:189], v[54:57]
	v_mfma_f32_16x16x32_bf16 v[50:53], v[158:161], v[186:189], v[50:53]
	v_mfma_f32_16x16x32_bf16 v[46:49], v[150:153], v[182:185], v[46:49]
	v_mfma_f32_16x16x32_bf16 v[42:45], v[158:161], v[182:185], v[42:45]
	v_mfma_f32_16x16x32_bf16 v[38:41], v[150:153], v[178:181], v[38:41]
	v_mfma_f32_16x16x32_bf16 v[34:37], v[158:161], v[178:181], v[34:37]
	s_setprio 0
	s_setprio 1
	v_mfma_f32_16x16x32_bf16 v[30:33], v[130:133], v[174:177], v[30:33]
	v_mfma_f32_16x16x32_bf16 v[26:29], v[138:141], v[174:177], v[26:29]
	v_mfma_f32_16x16x32_bf16 v[22:25], v[130:133], v[170:173], v[22:25]
	v_mfma_f32_16x16x32_bf16 v[18:21], v[138:141], v[170:173], v[18:21]
	v_mfma_f32_16x16x32_bf16 v[14:17], v[130:133], v[166:169], v[14:17]
	v_mfma_f32_16x16x32_bf16 v[10:13], v[138:141], v[166:169], v[10:13]
	v_mfma_f32_16x16x32_bf16 v[6:9], v[130:133], v[162:165], v[6:9]
	v_mfma_f32_16x16x32_bf16 v[2:5], v[138:141], v[162:165], v[2:5]
	v_mfma_f32_16x16x32_bf16 v[30:33], v[134:137], v[190:193], v[30:33]
	v_mfma_f32_16x16x32_bf16 v[26:29], v[142:145], v[190:193], v[26:29]
	v_mfma_f32_16x16x32_bf16 v[22:25], v[134:137], v[186:189], v[22:25]
	v_mfma_f32_16x16x32_bf16 v[18:21], v[142:145], v[186:189], v[18:21]
	v_mfma_f32_16x16x32_bf16 v[14:17], v[134:137], v[182:185], v[14:17]
	v_mfma_f32_16x16x32_bf16 v[10:13], v[142:145], v[182:185], v[10:13]
	v_mfma_f32_16x16x32_bf16 v[6:9], v[134:137], v[178:181], v[6:9]
	v_mfma_f32_16x16x32_bf16 v[2:5], v[142:145], v[178:181], v[2:5]
	s_setprio 0
.LBB0_907:
	s_and_b64 vcc, s[40:41], s[72:73]
	v_cndmask_b32_e64 v131, v209, 0, vcc
	v_cndmask_b32_e32 v130, v208, v198, vcc
	v_lshl_add_u64 v[234:235], s[70:71], 0, v[130:131]
	s_barrier
	s_mov_b32 m0, s8
	s_nop 0
	global_load_lds_dwordx4 v194, s[98:99]
	s_mov_b32 m0, s13
	s_nop 0
	global_load_lds_dwordx4 v196, s[98:99]
	v_add_u32_e32 v130, 0x18000, v224
	v_add_u32_e32 v142, 0x1c000, v224
	ds_read_b128 v[146:149], v130
	ds_read_b128 v[150:153], v130 offset:1024
	ds_read_b128 v[154:157], v130 offset:2048
	ds_read_b128 v[158:161], v130 offset:3072
	ds_read_b128 v[130:133], v142
	ds_read_b128 v[134:137], v142 offset:1024
	ds_read_b128 v[138:141], v142 offset:2048
	ds_read_b128 v[142:145], v142 offset:3072
	s_mov_b32 m0, s14
	v_lshl_add_u64 v[236:237], v[234:235], 0, v[194:195]
	s_waitcnt lgkmcnt(0)
	ds_read_b128 v[174:177], v228 offset:32768
	ds_read_b128 v[190:193], v228 offset:33792
	ds_read_b128 v[170:173], v228 offset:34816
	ds_read_b128 v[186:189], v228 offset:35840
	ds_read_b128 v[166:169], v228 offset:36864
	ds_read_b128 v[182:185], v228 offset:37888
	ds_read_b128 v[162:165], v228 offset:38912
	ds_read_b128 v[178:181], v228 offset:39936
	global_load_lds_dwordx4 v[236:237], off
	v_lshl_add_u64 v[234:235], v[234:235], 0, v[196:197]
	s_mov_b32 m0, s15
	s_nop 0
	global_load_lds_dwordx4 v[234:235], off
	s_waitcnt vmcnt(8)
	s_waitcnt lgkmcnt(0)
	s_barrier
	s_setprio 1
	s_waitcnt lgkmcnt(0)
	v_mfma_f32_16x16x32_bf16 v[126:129], v[146:149], v[174:177], v[126:129]
	v_mfma_f32_16x16x32_bf16 v[122:125], v[154:157], v[174:177], v[122:125]
	v_mfma_f32_16x16x32_bf16 v[118:121], v[146:149], v[170:173], v[118:121]
	v_mfma_f32_16x16x32_bf16 v[114:117], v[154:157], v[170:173], v[114:117]
	v_mfma_f32_16x16x32_bf16 v[110:113], v[146:149], v[166:169], v[110:113]
	v_mfma_f32_16x16x32_bf16 v[106:109], v[154:157], v[166:169], v[106:109]
	v_mfma_f32_16x16x32_bf16 v[102:105], v[146:149], v[162:165], v[102:105]
	v_mfma_f32_16x16x32_bf16 v[98:101], v[154:157], v[162:165], v[98:101]
	v_mfma_f32_16x16x32_bf16 v[126:129], v[150:153], v[190:193], v[126:129]
	v_mfma_f32_16x16x32_bf16 v[122:125], v[158:161], v[190:193], v[122:125]
	v_mfma_f32_16x16x32_bf16 v[118:121], v[150:153], v[186:189], v[118:121]
	v_mfma_f32_16x16x32_bf16 v[114:117], v[158:161], v[186:189], v[114:117]
	v_mfma_f32_16x16x32_bf16 v[110:113], v[150:153], v[182:185], v[110:113]
	v_mfma_f32_16x16x32_bf16 v[106:109], v[158:161], v[182:185], v[106:109]
	v_mfma_f32_16x16x32_bf16 v[102:105], v[150:153], v[178:181], v[102:105]
	v_mfma_f32_16x16x32_bf16 v[98:101], v[158:161], v[178:181], v[98:101]
	s_setprio 0
	s_setprio 1
	s_add_u32 s72, s68, 0xe0000
	s_addc_u32 s73, s69, 0
	s_add_u32 s70, s70, 0x220000
	s_addc_u32 s71, s71, 0
	v_mfma_f32_16x16x32_bf16 v[94:97], v[130:133], v[174:177], v[94:97]
	v_mfma_f32_16x16x32_bf16 v[90:93], v[138:141], v[174:177], v[90:93]
	v_mfma_f32_16x16x32_bf16 v[86:89], v[130:133], v[170:173], v[86:89]
	v_mfma_f32_16x16x32_bf16 v[82:85], v[138:141], v[170:173], v[82:85]
	v_mfma_f32_16x16x32_bf16 v[78:81], v[130:133], v[166:169], v[78:81]
	v_mfma_f32_16x16x32_bf16 v[74:77], v[138:141], v[166:169], v[74:77]
	v_mfma_f32_16x16x32_bf16 v[70:73], v[130:133], v[162:165], v[70:73]
	v_mfma_f32_16x16x32_bf16 v[66:69], v[138:141], v[162:165], v[66:69]
	v_mfma_f32_16x16x32_bf16 v[94:97], v[134:137], v[190:193], v[94:97]
	v_mfma_f32_16x16x32_bf16 v[90:93], v[142:145], v[190:193], v[90:93]
	v_mfma_f32_16x16x32_bf16 v[86:89], v[134:137], v[186:189], v[86:89]
	v_mfma_f32_16x16x32_bf16 v[82:85], v[142:145], v[186:189], v[82:85]
	v_mfma_f32_16x16x32_bf16 v[78:81], v[134:137], v[182:185], v[78:81]
	v_mfma_f32_16x16x32_bf16 v[74:77], v[142:145], v[182:185], v[74:77]
	v_mfma_f32_16x16x32_bf16 v[70:73], v[134:137], v[178:181], v[70:73]
	v_mfma_f32_16x16x32_bf16 v[66:69], v[142:145], v[178:181], v[66:69]
	s_setprio 0
	s_barrier
	s_and_b64 vcc, exec, s[42:43]
	s_cbranch_vccnz .LBB0_909
	ds_read_b128 v[174:177], v228 offset:49152
	ds_read_b128 v[190:193], v228 offset:50176
	ds_read_b128 v[170:173], v228 offset:51200
	ds_read_b128 v[186:189], v228 offset:52224
	ds_read_b128 v[166:169], v228 offset:53248
	ds_read_b128 v[182:185], v228 offset:54272
	ds_read_b128 v[162:165], v228 offset:55296
	ds_read_b128 v[178:181], v228 offset:56320
.LBB0_909:
	s_mov_b32 m0, s16
	s_add_u32 s68, s68, 0xe4000
	global_load_lds_dwordx4 v194, s[72:73]
	s_mov_b32 m0, s17
	s_addc_u32 s69, s69, 0
	global_load_lds_dwordx4 v196, s[72:73]
	s_mov_b32 m0, s54
	s_and_b64 vcc, exec, s[42:43]
	global_load_lds_dwordx4 v194, s[68:69]
	s_mov_b32 m0, s55
	s_nop 0
	global_load_lds_dwordx4 v196, s[68:69]
	s_mov_b64 s[100:101], s[70:71]
	s_waitcnt vmcnt(6)
	s_waitcnt lgkmcnt(0)
	s_barrier
	s_cbranch_vccnz .LBB0_902
	s_setprio 1
	s_waitcnt lgkmcnt(0)
	v_mfma_f32_16x16x32_bf16 v[62:65], v[146:149], v[174:177], v[62:65]
	v_mfma_f32_16x16x32_bf16 v[58:61], v[154:157], v[174:177], v[58:61]
	v_mfma_f32_16x16x32_bf16 v[54:57], v[146:149], v[170:173], v[54:57]
	v_mfma_f32_16x16x32_bf16 v[50:53], v[154:157], v[170:173], v[50:53]
	v_mfma_f32_16x16x32_bf16 v[46:49], v[146:149], v[166:169], v[46:49]
	v_mfma_f32_16x16x32_bf16 v[42:45], v[154:157], v[166:169], v[42:45]
	v_mfma_f32_16x16x32_bf16 v[38:41], v[146:149], v[162:165], v[38:41]
	v_mfma_f32_16x16x32_bf16 v[34:37], v[154:157], v[162:165], v[34:37]
	v_mfma_f32_16x16x32_bf16 v[62:65], v[150:153], v[190:193], v[62:65]
	v_mfma_f32_16x16x32_bf16 v[58:61], v[158:161], v[190:193], v[58:61]
	v_mfma_f32_16x16x32_bf16 v[54:57], v[150:153], v[186:189], v[54:57]
	v_mfma_f32_16x16x32_bf16 v[50:53], v[158:161], v[186:189], v[50:53]
	v_mfma_f32_16x16x32_bf16 v[46:49], v[150:153], v[182:185], v[46:49]
	v_mfma_f32_16x16x32_bf16 v[42:45], v[158:161], v[182:185], v[42:45]
	v_mfma_f32_16x16x32_bf16 v[38:41], v[150:153], v[178:181], v[38:41]
	v_mfma_f32_16x16x32_bf16 v[34:37], v[158:161], v[178:181], v[34:37]
	s_setprio 0
	s_setprio 1
	v_mfma_f32_16x16x32_bf16 v[30:33], v[130:133], v[174:177], v[30:33]
	v_mfma_f32_16x16x32_bf16 v[26:29], v[138:141], v[174:177], v[26:29]
	v_mfma_f32_16x16x32_bf16 v[22:25], v[130:133], v[170:173], v[22:25]
	v_mfma_f32_16x16x32_bf16 v[18:21], v[138:141], v[170:173], v[18:21]
	v_mfma_f32_16x16x32_bf16 v[14:17], v[130:133], v[166:169], v[14:17]
	v_mfma_f32_16x16x32_bf16 v[10:13], v[138:141], v[166:169], v[10:13]
	v_mfma_f32_16x16x32_bf16 v[6:9], v[130:133], v[162:165], v[6:9]
	v_mfma_f32_16x16x32_bf16 v[2:5], v[138:141], v[162:165], v[2:5]
	v_mfma_f32_16x16x32_bf16 v[30:33], v[134:137], v[190:193], v[30:33]
	v_mfma_f32_16x16x32_bf16 v[26:29], v[142:145], v[190:193], v[26:29]
	v_mfma_f32_16x16x32_bf16 v[22:25], v[134:137], v[186:189], v[22:25]
	v_mfma_f32_16x16x32_bf16 v[18:21], v[142:145], v[186:189], v[18:21]
	v_mfma_f32_16x16x32_bf16 v[14:17], v[134:137], v[182:185], v[14:17]
	v_mfma_f32_16x16x32_bf16 v[10:13], v[142:145], v[182:185], v[10:13]
	v_mfma_f32_16x16x32_bf16 v[6:9], v[134:137], v[178:181], v[6:9]
	v_mfma_f32_16x16x32_bf16 v[2:5], v[142:145], v[178:181], v[2:5]
	s_setprio 0
	s_branch .LBB0_902

.LBB0_1289:
	s_mov_b32 m0, s27
	s_nop 0
	global_load_lds_dwordx4 v194, s[100:101]
	s_mov_b32 m0, s54
	s_nop 0
	global_load_lds_dwordx4 v196, s[100:101]
	v_add_u32_e32 v142, 0x14000, v229
	ds_read_b128 v[146:149], v230
	ds_read_b128 v[150:153], v230 offset:1024
	ds_read_b128 v[154:157], v230 offset:2048
	ds_read_b128 v[158:161], v230 offset:3072
	ds_read_b128 v[130:133], v142
	ds_read_b128 v[134:137], v142 offset:1024
	ds_read_b128 v[138:141], v142 offset:2048
	ds_read_b128 v[142:145], v142 offset:3072
	v_lshl_add_u64 v[234:235], v[222:223], 0, s[48:49]
	s_add_i32 m0, s8, 0xc000
	s_waitcnt lgkmcnt(0)
	ds_read_b128 v[174:177], v231
	ds_read_b128 v[190:193], v231 offset:1024
	ds_read_b128 v[170:173], v231 offset:2048
	ds_read_b128 v[186:189], v231 offset:3072
	ds_read_b128 v[166:169], v231 offset:4096
	ds_read_b128 v[182:185], v231 offset:5120
	ds_read_b128 v[162:165], v231 offset:6144
	ds_read_b128 v[178:181], v231 offset:7168
	global_load_lds_dwordx4 v[234:235], off
	v_lshl_add_u64 v[234:235], v[224:225], 0, s[48:49]
	s_add_i32 m0, s8, 0xe000
	s_nop 0
	global_load_lds_dwordx4 v[234:235], off
	s_waitcnt vmcnt(8)
	s_waitcnt lgkmcnt(0)
	s_barrier
	s_setprio 1
	s_waitcnt lgkmcnt(0)
	v_mfma_f32_16x16x32_bf16 v[126:129], v[146:149], v[174:177], v[126:129]
	v_mfma_f32_16x16x32_bf16 v[122:125], v[154:157], v[174:177], v[122:125]
	v_mfma_f32_16x16x32_bf16 v[118:121], v[146:149], v[170:173], v[118:121]
	v_mfma_f32_16x16x32_bf16 v[110:113], v[154:157], v[170:173], v[110:113]
	v_mfma_f32_16x16x32_bf16 v[102:105], v[146:149], v[166:169], v[102:105]
	v_mfma_f32_16x16x32_bf16 v[94:97], v[154:157], v[166:169], v[94:97]
	v_mfma_f32_16x16x32_bf16 v[86:89], v[146:149], v[162:165], v[86:89]
	v_mfma_f32_16x16x32_bf16 v[78:81], v[154:157], v[162:165], v[78:81]
	v_mfma_f32_16x16x32_bf16 v[126:129], v[150:153], v[190:193], v[126:129]
	v_mfma_f32_16x16x32_bf16 v[122:125], v[158:161], v[190:193], v[122:125]
	v_mfma_f32_16x16x32_bf16 v[118:121], v[150:153], v[186:189], v[118:121]
	v_mfma_f32_16x16x32_bf16 v[110:113], v[158:161], v[186:189], v[110:113]
	v_mfma_f32_16x16x32_bf16 v[102:105], v[150:153], v[182:185], v[102:105]
	v_mfma_f32_16x16x32_bf16 v[94:97], v[158:161], v[182:185], v[94:97]
	v_mfma_f32_16x16x32_bf16 v[86:89], v[150:153], v[178:181], v[86:89]
	v_mfma_f32_16x16x32_bf16 v[78:81], v[158:161], v[178:181], v[78:81]
	s_setprio 0
	s_setprio 1
	s_add_u32 s52, s36, s48
	s_addc_u32 s53, s37, s49
	s_add_u32 s56, s52, 0x440000
	s_addc_u32 s57, s53, 0
	s_cmp_eq_u32 s48, 0x3fc0000
	s_cselect_b64 s[58:59], -1, 0
	s_and_b64 s[52:53], s[58:59], exec
	s_cselect_b32 s53, s31, s63
	s_cselect_b32 s52, s61, s62
	s_cselect_b32 s57, s19, s57
	s_cselect_b32 s56, s29, s56
	v_mfma_f32_16x16x32_bf16 v[114:117], v[130:133], v[174:177], v[114:117]
	v_mfma_f32_16x16x32_bf16 v[106:109], v[138:141], v[174:177], v[106:109]
	v_mfma_f32_16x16x32_bf16 v[98:101], v[130:133], v[170:173], v[98:101]
	v_mfma_f32_16x16x32_bf16 v[90:93], v[138:141], v[170:173], v[90:93]
	v_mfma_f32_16x16x32_bf16 v[82:85], v[130:133], v[166:169], v[82:85]
	v_mfma_f32_16x16x32_bf16 v[74:77], v[138:141], v[166:169], v[74:77]
	v_mfma_f32_16x16x32_bf16 v[70:73], v[130:133], v[162:165], v[70:73]
	v_mfma_f32_16x16x32_bf16 v[66:69], v[138:141], v[162:165], v[66:69]
	v_mfma_f32_16x16x32_bf16 v[114:117], v[134:137], v[190:193], v[114:117]
	v_mfma_f32_16x16x32_bf16 v[106:109], v[142:145], v[190:193], v[106:109]
	v_mfma_f32_16x16x32_bf16 v[98:101], v[134:137], v[186:189], v[98:101]
	v_mfma_f32_16x16x32_bf16 v[90:93], v[142:145], v[186:189], v[90:93]
	v_mfma_f32_16x16x32_bf16 v[82:85], v[134:137], v[182:185], v[82:85]
	v_mfma_f32_16x16x32_bf16 v[74:77], v[142:145], v[182:185], v[74:77]
	v_mfma_f32_16x16x32_bf16 v[70:73], v[134:137], v[178:181], v[70:73]
	v_mfma_f32_16x16x32_bf16 v[66:69], v[142:145], v[178:181], v[66:69]
	s_setprio 0
	s_barrier
	v_cndmask_b32_e64 v233, 0, 1, s[40:41]
	v_cmp_ne_u32_e64 s[42:43], 1, v233
	s_andn2_b64 vcc, exec, s[40:41]
	s_cbranch_vccnz .LBB0_1291
	ds_read_b128 v[174:177], v231 offset:16384
	ds_read_b128 v[190:193], v231 offset:17408
	ds_read_b128 v[170:173], v231 offset:18432
	ds_read_b128 v[186:189], v231 offset:19456
	ds_read_b128 v[166:169], v231 offset:20480
	ds_read_b128 v[182:185], v231 offset:21504
	ds_read_b128 v[162:165], v231 offset:22528
	ds_read_b128 v[178:181], v231 offset:23552
.LBB0_1291:
	s_mov_b32 m0, s9
	s_add_u32 s68, s52, 0x4000
	global_load_lds_dwordx4 v194, s[52:53]
	s_mov_b32 m0, s10
	s_addc_u32 s69, s53, 0
	global_load_lds_dwordx4 v196, s[52:53]
	s_mov_b32 m0, s11
	s_and_b64 vcc, exec, s[42:43]
	global_load_lds_dwordx4 v194, s[68:69]
	s_mov_b32 m0, s12
	s_nop 0
	global_load_lds_dwordx4 v196, s[68:69]
	s_mov_b64 s[98:99], s[56:57]
	s_waitcnt vmcnt(6)
	s_waitcnt lgkmcnt(0)
	s_barrier
	s_cbranch_vccnz .LBB0_1293
	s_setprio 1
	s_waitcnt lgkmcnt(0)
	v_mfma_f32_16x16x32_bf16 v[62:65], v[146:149], v[174:177], v[62:65]
	v_mfma_f32_16x16x32_bf16 v[58:61], v[154:157], v[174:177], v[58:61]
	v_mfma_f32_16x16x32_bf16 v[46:49], v[146:149], v[170:173], v[46:49]
	v_mfma_f32_16x16x32_bf16 v[42:45], v[154:157], v[170:173], v[42:45]
	v_mfma_f32_16x16x32_bf16 v[30:33], v[146:149], v[166:169], v[30:33]
	v_mfma_f32_16x16x32_bf16 v[26:29], v[154:157], v[166:169], v[26:29]
	v_mfma_f32_16x16x32_bf16 v[14:17], v[146:149], v[162:165], v[14:17]
	v_mfma_f32_16x16x32_bf16 v[10:13], v[154:157], v[162:165], v[10:13]
	v_mfma_f32_16x16x32_bf16 v[62:65], v[150:153], v[190:193], v[62:65]
	v_mfma_f32_16x16x32_bf16 v[58:61], v[158:161], v[190:193], v[58:61]
	v_mfma_f32_16x16x32_bf16 v[46:49], v[150:153], v[186:189], v[46:49]
	v_mfma_f32_16x16x32_bf16 v[42:45], v[158:161], v[186:189], v[42:45]
	v_mfma_f32_16x16x32_bf16 v[30:33], v[150:153], v[182:185], v[30:33]
	v_mfma_f32_16x16x32_bf16 v[26:29], v[158:161], v[182:185], v[26:29]
	v_mfma_f32_16x16x32_bf16 v[14:17], v[150:153], v[178:181], v[14:17]
	v_mfma_f32_16x16x32_bf16 v[10:13], v[158:161], v[178:181], v[10:13]
	s_setprio 0
	s_setprio 1
	v_mfma_f32_16x16x32_bf16 v[54:57], v[130:133], v[174:177], v[54:57]
	v_mfma_f32_16x16x32_bf16 v[50:53], v[138:141], v[174:177], v[50:53]
	v_mfma_f32_16x16x32_bf16 v[38:41], v[130:133], v[170:173], v[38:41]
	v_mfma_f32_16x16x32_bf16 v[34:37], v[138:141], v[170:173], v[34:37]
	v_mfma_f32_16x16x32_bf16 v[22:25], v[130:133], v[166:169], v[22:25]
	v_mfma_f32_16x16x32_bf16 v[18:21], v[138:141], v[166:169], v[18:21]
	v_mfma_f32_16x16x32_bf16 v[6:9], v[130:133], v[162:165], v[6:9]
	v_mfma_f32_16x16x32_bf16 v[2:5], v[138:141], v[162:165], v[2:5]
	v_mfma_f32_16x16x32_bf16 v[54:57], v[134:137], v[190:193], v[54:57]
	v_mfma_f32_16x16x32_bf16 v[50:53], v[142:145], v[190:193], v[50:53]
	v_mfma_f32_16x16x32_bf16 v[38:41], v[134:137], v[186:189], v[38:41]
	v_mfma_f32_16x16x32_bf16 v[34:37], v[142:145], v[186:189], v[34:37]
	v_mfma_f32_16x16x32_bf16 v[22:25], v[134:137], v[182:185], v[22:25]
	v_mfma_f32_16x16x32_bf16 v[18:21], v[142:145], v[182:185], v[18:21]
	v_mfma_f32_16x16x32_bf16 v[6:9], v[134:137], v[178:181], v[6:9]
	v_mfma_f32_16x16x32_bf16 v[2:5], v[142:145], v[178:181], v[2:5]
	s_setprio 0
.LBB0_1293:
	s_and_b64 vcc, s[34:35], s[58:59]
	v_cndmask_b32_e64 v131, v221, 0, vcc
	v_cndmask_b32_e32 v130, v220, v198, vcc
	v_lshl_add_u64 v[234:235], s[56:57], 0, v[130:131]
	s_barrier
	s_mov_b32 m0, s8
	s_nop 0
	global_load_lds_dwordx4 v194, s[98:99]
	s_mov_b32 m0, s13
	s_nop 0
	global_load_lds_dwordx4 v196, s[98:99]
	v_add_u32_e32 v130, 0x18000, v229
	v_add_u32_e32 v142, 0x1c000, v229
	ds_read_b128 v[146:149], v130
	ds_read_b128 v[150:153], v130 offset:1024
	ds_read_b128 v[154:157], v130 offset:2048
	ds_read_b128 v[158:161], v130 offset:3072
	ds_read_b128 v[130:133], v142
	ds_read_b128 v[134:137], v142 offset:1024
	ds_read_b128 v[138:141], v142 offset:2048
	ds_read_b128 v[142:145], v142 offset:3072
	s_mov_b32 m0, s14
	v_lshl_add_u64 v[236:237], v[234:235], 0, v[194:195]
	s_waitcnt lgkmcnt(0)
	ds_read_b128 v[174:177], v231 offset:32768
	ds_read_b128 v[190:193], v231 offset:33792
	ds_read_b128 v[170:173], v231 offset:34816
	ds_read_b128 v[186:189], v231 offset:35840
	ds_read_b128 v[166:169], v231 offset:36864
	ds_read_b128 v[182:185], v231 offset:37888
	ds_read_b128 v[162:165], v231 offset:38912
	ds_read_b128 v[178:181], v231 offset:39936
	global_load_lds_dwordx4 v[236:237], off
	v_lshl_add_u64 v[234:235], v[234:235], 0, v[196:197]
	s_mov_b32 m0, s15
	s_nop 0
	global_load_lds_dwordx4 v[234:235], off
	s_waitcnt vmcnt(8)
	s_waitcnt lgkmcnt(0)
	s_barrier
	s_setprio 1
	s_waitcnt lgkmcnt(0)
	v_mfma_f32_16x16x32_bf16 v[126:129], v[146:149], v[174:177], v[126:129]
	v_mfma_f32_16x16x32_bf16 v[122:125], v[154:157], v[174:177], v[122:125]
	v_mfma_f32_16x16x32_bf16 v[118:121], v[146:149], v[170:173], v[118:121]
	v_mfma_f32_16x16x32_bf16 v[110:113], v[154:157], v[170:173], v[110:113]
	v_mfma_f32_16x16x32_bf16 v[102:105], v[146:149], v[166:169], v[102:105]
	v_mfma_f32_16x16x32_bf16 v[94:97], v[154:157], v[166:169], v[94:97]
	v_mfma_f32_16x16x32_bf16 v[86:89], v[146:149], v[162:165], v[86:89]
	v_mfma_f32_16x16x32_bf16 v[78:81], v[154:157], v[162:165], v[78:81]
	v_mfma_f32_16x16x32_bf16 v[126:129], v[150:153], v[190:193], v[126:129]
	v_mfma_f32_16x16x32_bf16 v[122:125], v[158:161], v[190:193], v[122:125]
	v_mfma_f32_16x16x32_bf16 v[118:121], v[150:153], v[186:189], v[118:121]
	v_mfma_f32_16x16x32_bf16 v[110:113], v[158:161], v[186:189], v[110:113]
	v_mfma_f32_16x16x32_bf16 v[102:105], v[150:153], v[182:185], v[102:105]
	v_mfma_f32_16x16x32_bf16 v[94:97], v[158:161], v[182:185], v[94:97]
	v_mfma_f32_16x16x32_bf16 v[86:89], v[150:153], v[178:181], v[86:89]
	v_mfma_f32_16x16x32_bf16 v[78:81], v[158:161], v[178:181], v[78:81]
	s_setprio 0
	s_setprio 1
	s_add_u32 s58, s52, 0x40000
	s_addc_u32 s59, s53, 0
	s_add_u32 s56, s56, 0x220000
	s_addc_u32 s57, s57, 0
	v_mfma_f32_16x16x32_bf16 v[114:117], v[130:133], v[174:177], v[114:117]
	v_mfma_f32_16x16x32_bf16 v[106:109], v[138:141], v[174:177], v[106:109]
	v_mfma_f32_16x16x32_bf16 v[98:101], v[130:133], v[170:173], v[98:101]
	v_mfma_f32_16x16x32_bf16 v[90:93], v[138:141], v[170:173], v[90:93]
	v_mfma_f32_16x16x32_bf16 v[82:85], v[130:133], v[166:169], v[82:85]
	v_mfma_f32_16x16x32_bf16 v[74:77], v[138:141], v[166:169], v[74:77]
	v_mfma_f32_16x16x32_bf16 v[70:73], v[130:133], v[162:165], v[70:73]
	v_mfma_f32_16x16x32_bf16 v[66:69], v[138:141], v[162:165], v[66:69]
	v_mfma_f32_16x16x32_bf16 v[114:117], v[134:137], v[190:193], v[114:117]
	v_mfma_f32_16x16x32_bf16 v[106:109], v[142:145], v[190:193], v[106:109]
	v_mfma_f32_16x16x32_bf16 v[98:101], v[134:137], v[186:189], v[98:101]
	v_mfma_f32_16x16x32_bf16 v[90:93], v[142:145], v[186:189], v[90:93]
	v_mfma_f32_16x16x32_bf16 v[82:85], v[134:137], v[182:185], v[82:85]
	v_mfma_f32_16x16x32_bf16 v[74:77], v[142:145], v[182:185], v[74:77]
	v_mfma_f32_16x16x32_bf16 v[70:73], v[134:137], v[178:181], v[70:73]
	v_mfma_f32_16x16x32_bf16 v[66:69], v[142:145], v[178:181], v[66:69]
	s_setprio 0
	s_barrier
	s_and_b64 vcc, exec, s[42:43]
	s_cbranch_vccnz .LBB0_1295
	ds_read_b128 v[174:177], v231 offset:49152
	ds_read_b128 v[190:193], v231 offset:50176
	ds_read_b128 v[170:173], v231 offset:51200
	ds_read_b128 v[186:189], v231 offset:52224
	ds_read_b128 v[166:169], v231 offset:53248
	ds_read_b128 v[182:185], v231 offset:54272
	ds_read_b128 v[162:165], v231 offset:55296
	ds_read_b128 v[178:181], v231 offset:56320
.LBB0_1295:
	s_mov_b32 m0, s16
	s_add_u32 s52, s52, 0x44000
	global_load_lds_dwordx4 v194, s[58:59]
	s_mov_b32 m0, s17
	s_addc_u32 s53, s53, 0
	global_load_lds_dwordx4 v196, s[58:59]
	s_mov_b32 m0, s55
	s_and_b64 vcc, exec, s[42:43]
	global_load_lds_dwordx4 v194, s[52:53]
	s_mov_b32 m0, s60
	s_nop 0
	global_load_lds_dwordx4 v196, s[52:53]
	s_mov_b64 s[100:101], s[56:57]
	s_waitcnt vmcnt(6)
	s_waitcnt lgkmcnt(0)
	s_barrier
	s_cbranch_vccnz .LBB0_1288
	s_setprio 1
	s_waitcnt lgkmcnt(0)
	v_mfma_f32_16x16x32_bf16 v[62:65], v[146:149], v[174:177], v[62:65]
	v_mfma_f32_16x16x32_bf16 v[58:61], v[154:157], v[174:177], v[58:61]
	v_mfma_f32_16x16x32_bf16 v[46:49], v[146:149], v[170:173], v[46:49]
	v_mfma_f32_16x16x32_bf16 v[42:45], v[154:157], v[170:173], v[42:45]
	v_mfma_f32_16x16x32_bf16 v[30:33], v[146:149], v[166:169], v[30:33]
	v_mfma_f32_16x16x32_bf16 v[26:29], v[154:157], v[166:169], v[26:29]
	v_mfma_f32_16x16x32_bf16 v[14:17], v[146:149], v[162:165], v[14:17]
	v_mfma_f32_16x16x32_bf16 v[10:13], v[154:157], v[162:165], v[10:13]
	v_mfma_f32_16x16x32_bf16 v[62:65], v[150:153], v[190:193], v[62:65]
	v_mfma_f32_16x16x32_bf16 v[58:61], v[158:161], v[190:193], v[58:61]
	v_mfma_f32_16x16x32_bf16 v[46:49], v[150:153], v[186:189], v[46:49]
	v_mfma_f32_16x16x32_bf16 v[42:45], v[158:161], v[186:189], v[42:45]
	v_mfma_f32_16x16x32_bf16 v[30:33], v[150:153], v[182:185], v[30:33]
	v_mfma_f32_16x16x32_bf16 v[26:29], v[158:161], v[182:185], v[26:29]
	v_mfma_f32_16x16x32_bf16 v[14:17], v[150:153], v[178:181], v[14:17]
	v_mfma_f32_16x16x32_bf16 v[10:13], v[158:161], v[178:181], v[10:13]
	s_setprio 0
	s_setprio 1
	v_mfma_f32_16x16x32_bf16 v[54:57], v[130:133], v[174:177], v[54:57]
	v_mfma_f32_16x16x32_bf16 v[50:53], v[138:141], v[174:177], v[50:53]
	v_mfma_f32_16x16x32_bf16 v[38:41], v[130:133], v[170:173], v[38:41]
	v_mfma_f32_16x16x32_bf16 v[34:37], v[138:141], v[170:173], v[34:37]
	v_mfma_f32_16x16x32_bf16 v[22:25], v[130:133], v[166:169], v[22:25]
	v_mfma_f32_16x16x32_bf16 v[18:21], v[138:141], v[166:169], v[18:21]
	v_mfma_f32_16x16x32_bf16 v[6:9], v[130:133], v[162:165], v[6:9]
	v_mfma_f32_16x16x32_bf16 v[2:5], v[138:141], v[162:165], v[2:5]
	v_mfma_f32_16x16x32_bf16 v[54:57], v[134:137], v[190:193], v[54:57]
	v_mfma_f32_16x16x32_bf16 v[50:53], v[142:145], v[190:193], v[50:53]
	v_mfma_f32_16x16x32_bf16 v[38:41], v[134:137], v[186:189], v[38:41]
	v_mfma_f32_16x16x32_bf16 v[34:37], v[142:145], v[186:189], v[34:37]
	v_mfma_f32_16x16x32_bf16 v[22:25], v[134:137], v[182:185], v[22:25]
	v_mfma_f32_16x16x32_bf16 v[18:21], v[142:145], v[182:185], v[18:21]
	v_mfma_f32_16x16x32_bf16 v[6:9], v[134:137], v[178:181], v[6:9]
	v_mfma_f32_16x16x32_bf16 v[2:5], v[142:145], v[178:181], v[2:5]
	s_setprio 0
	s_branch .LBB0_1288

.LBB0_1612:
	s_mov_b32 m0, s54
	s_nop 0
	global_load_lds_dwordx4 v194, s[100:101]
	s_mov_b32 m0, s55
	s_nop 0
	global_load_lds_dwordx4 v196, s[100:101]
	v_add_u32_e32 v1, 0x10000, v232
	ds_read_b128 v[146:149], v1
	ds_read_b128 v[150:153], v1 offset:1024
	ds_read_b128 v[154:157], v1 offset:2048
	ds_read_b128 v[158:161], v1 offset:3072
	v_add_u32_e32 v1, 0x14000, v232
	ds_read_b128 v[130:133], v1
	ds_read_b128 v[134:137], v1 offset:1024
	ds_read_b128 v[138:141], v1 offset:2048
	ds_read_b128 v[142:145], v1 offset:3072
	v_lshl_add_u64 v[236:237], v[226:227], 0, s[48:49]
	s_add_i32 m0, s9, 0xc000
	s_waitcnt lgkmcnt(0)
	ds_read_b128 v[174:177], v233
	ds_read_b128 v[190:193], v233 offset:1024
	ds_read_b128 v[170:173], v233 offset:2048
	ds_read_b128 v[186:189], v233 offset:3072
	ds_read_b128 v[166:169], v233 offset:4096
	ds_read_b128 v[182:185], v233 offset:5120
	ds_read_b128 v[162:165], v233 offset:6144
	ds_read_b128 v[178:181], v233 offset:7168
	global_load_lds_dwordx4 v[236:237], off
	v_lshl_add_u64 v[236:237], v[228:229], 0, s[48:49]
	s_add_i32 m0, s9, 0xe000
	s_nop 0
	global_load_lds_dwordx4 v[236:237], off
	s_waitcnt vmcnt(8)
	s_waitcnt lgkmcnt(0)
	s_barrier
	s_setprio 1
	s_waitcnt lgkmcnt(0)
	v_mfma_f32_16x16x32_bf16 v[126:129], v[146:149], v[174:177], v[126:129]
	v_mfma_f32_16x16x32_bf16 v[122:125], v[154:157], v[174:177], v[122:125]
	v_mfma_f32_16x16x32_bf16 v[118:121], v[146:149], v[170:173], v[118:121]
	v_mfma_f32_16x16x32_bf16 v[110:113], v[154:157], v[170:173], v[110:113]
	v_mfma_f32_16x16x32_bf16 v[102:105], v[146:149], v[166:169], v[102:105]
	v_mfma_f32_16x16x32_bf16 v[94:97], v[154:157], v[166:169], v[94:97]
	v_mfma_f32_16x16x32_bf16 v[86:89], v[146:149], v[162:165], v[86:89]
	v_mfma_f32_16x16x32_bf16 v[78:81], v[154:157], v[162:165], v[78:81]
	v_mfma_f32_16x16x32_bf16 v[126:129], v[150:153], v[190:193], v[126:129]
	v_mfma_f32_16x16x32_bf16 v[122:125], v[158:161], v[190:193], v[122:125]
	v_mfma_f32_16x16x32_bf16 v[118:121], v[150:153], v[186:189], v[118:121]
	v_mfma_f32_16x16x32_bf16 v[110:113], v[158:161], v[186:189], v[110:113]
	v_mfma_f32_16x16x32_bf16 v[102:105], v[150:153], v[182:185], v[102:105]
	v_mfma_f32_16x16x32_bf16 v[94:97], v[158:161], v[182:185], v[94:97]
	v_mfma_f32_16x16x32_bf16 v[86:89], v[150:153], v[178:181], v[86:89]
	v_mfma_f32_16x16x32_bf16 v[78:81], v[158:161], v[178:181], v[78:81]
	s_setprio 0
	s_setprio 1
	s_add_u32 s50, s46, s48
	s_addc_u32 s51, s47, s49
	s_add_u32 s52, s50, 0x440000
	s_addc_u32 s53, s51, 0
	s_cmp_eq_u32 s48, 0x3fc0000
	s_cselect_b64 s[56:57], -1, 0
	s_and_b64 s[50:51], s[56:57], exec
	s_cselect_b32 s51, s31, s61
	s_cselect_b32 s50, s35, s60
	s_cselect_b32 s53, s19, s53
	s_cselect_b32 s52, s20, s52
	v_mfma_f32_16x16x32_bf16 v[114:117], v[130:133], v[174:177], v[114:117]
	v_mfma_f32_16x16x32_bf16 v[106:109], v[138:141], v[174:177], v[106:109]
	v_mfma_f32_16x16x32_bf16 v[98:101], v[130:133], v[170:173], v[98:101]
	v_mfma_f32_16x16x32_bf16 v[90:93], v[138:141], v[170:173], v[90:93]
	v_mfma_f32_16x16x32_bf16 v[82:85], v[130:133], v[166:169], v[82:85]
	v_mfma_f32_16x16x32_bf16 v[74:77], v[138:141], v[166:169], v[74:77]
	v_mfma_f32_16x16x32_bf16 v[70:73], v[130:133], v[162:165], v[70:73]
	v_mfma_f32_16x16x32_bf16 v[66:69], v[138:141], v[162:165], v[66:69]
	v_mfma_f32_16x16x32_bf16 v[114:117], v[134:137], v[190:193], v[114:117]
	v_mfma_f32_16x16x32_bf16 v[106:109], v[142:145], v[190:193], v[106:109]
	v_mfma_f32_16x16x32_bf16 v[98:101], v[134:137], v[186:189], v[98:101]
	v_mfma_f32_16x16x32_bf16 v[90:93], v[142:145], v[186:189], v[90:93]
	v_mfma_f32_16x16x32_bf16 v[82:85], v[134:137], v[182:185], v[82:85]
	v_mfma_f32_16x16x32_bf16 v[74:77], v[142:145], v[182:185], v[74:77]
	v_mfma_f32_16x16x32_bf16 v[70:73], v[134:137], v[178:181], v[70:73]
	v_mfma_f32_16x16x32_bf16 v[66:69], v[142:145], v[178:181], v[66:69]
	s_setprio 0
	s_barrier
	v_cndmask_b32_e64 v1, 0, 1, s[40:41]
	v_cmp_ne_u32_e64 s[42:43], 1, v1
	s_andn2_b64 vcc, exec, s[40:41]
	s_cbranch_vccnz .LBB0_1614
	ds_read_b128 v[174:177], v233 offset:16384
	ds_read_b128 v[190:193], v233 offset:17408
	ds_read_b128 v[170:173], v233 offset:18432
	ds_read_b128 v[186:189], v233 offset:19456
	ds_read_b128 v[166:169], v233 offset:20480
	ds_read_b128 v[182:185], v233 offset:21504
	ds_read_b128 v[162:165], v233 offset:22528
	ds_read_b128 v[178:181], v233 offset:23552
.LBB0_1614:
	s_mov_b32 m0, s10
	s_add_u32 s68, s50, 0x4000
	global_load_lds_dwordx4 v194, s[50:51]
	s_mov_b32 m0, s11
	s_addc_u32 s69, s51, 0
	global_load_lds_dwordx4 v196, s[50:51]
	s_mov_b32 m0, s12
	s_and_b64 vcc, exec, s[42:43]
	global_load_lds_dwordx4 v194, s[68:69]
	s_mov_b32 m0, s13
	s_nop 0
	global_load_lds_dwordx4 v196, s[68:69]
	s_mov_b64 s[98:99], s[52:53]
	s_waitcnt vmcnt(6)
	s_waitcnt lgkmcnt(0)
	s_barrier
	s_cbranch_vccnz .LBB0_1616
	s_setprio 1
	s_waitcnt lgkmcnt(0)
	v_mfma_f32_16x16x32_bf16 v[62:65], v[146:149], v[174:177], v[62:65]
	v_mfma_f32_16x16x32_bf16 v[58:61], v[154:157], v[174:177], v[58:61]
	v_mfma_f32_16x16x32_bf16 v[46:49], v[146:149], v[170:173], v[46:49]
	v_mfma_f32_16x16x32_bf16 v[42:45], v[154:157], v[170:173], v[42:45]
	v_mfma_f32_16x16x32_bf16 v[30:33], v[146:149], v[166:169], v[30:33]
	v_mfma_f32_16x16x32_bf16 v[26:29], v[154:157], v[166:169], v[26:29]
	v_mfma_f32_16x16x32_bf16 v[14:17], v[146:149], v[162:165], v[14:17]
	v_mfma_f32_16x16x32_bf16 v[10:13], v[154:157], v[162:165], v[10:13]
	v_mfma_f32_16x16x32_bf16 v[62:65], v[150:153], v[190:193], v[62:65]
	v_mfma_f32_16x16x32_bf16 v[58:61], v[158:161], v[190:193], v[58:61]
	v_mfma_f32_16x16x32_bf16 v[46:49], v[150:153], v[186:189], v[46:49]
	v_mfma_f32_16x16x32_bf16 v[42:45], v[158:161], v[186:189], v[42:45]
	v_mfma_f32_16x16x32_bf16 v[30:33], v[150:153], v[182:185], v[30:33]
	v_mfma_f32_16x16x32_bf16 v[26:29], v[158:161], v[182:185], v[26:29]
	v_mfma_f32_16x16x32_bf16 v[14:17], v[150:153], v[178:181], v[14:17]
	v_mfma_f32_16x16x32_bf16 v[10:13], v[158:161], v[178:181], v[10:13]
	s_setprio 0
	s_setprio 1
	v_mfma_f32_16x16x32_bf16 v[54:57], v[130:133], v[174:177], v[54:57]
	v_mfma_f32_16x16x32_bf16 v[50:53], v[138:141], v[174:177], v[50:53]
	v_mfma_f32_16x16x32_bf16 v[38:41], v[130:133], v[170:173], v[38:41]
	v_mfma_f32_16x16x32_bf16 v[34:37], v[138:141], v[170:173], v[34:37]
	v_mfma_f32_16x16x32_bf16 v[22:25], v[130:133], v[166:169], v[22:25]
	v_mfma_f32_16x16x32_bf16 v[18:21], v[138:141], v[166:169], v[18:21]
	v_mfma_f32_16x16x32_bf16 v[6:9], v[130:133], v[162:165], v[6:9]
	v_mfma_f32_16x16x32_bf16 v[2:5], v[138:141], v[162:165], v[2:5]
	v_mfma_f32_16x16x32_bf16 v[54:57], v[134:137], v[190:193], v[54:57]
	v_mfma_f32_16x16x32_bf16 v[50:53], v[142:145], v[190:193], v[50:53]
	v_mfma_f32_16x16x32_bf16 v[38:41], v[134:137], v[186:189], v[38:41]
	v_mfma_f32_16x16x32_bf16 v[34:37], v[142:145], v[186:189], v[34:37]
	v_mfma_f32_16x16x32_bf16 v[22:25], v[134:137], v[182:185], v[22:25]
	v_mfma_f32_16x16x32_bf16 v[18:21], v[142:145], v[182:185], v[18:21]
	v_mfma_f32_16x16x32_bf16 v[6:9], v[134:137], v[178:181], v[6:9]
	v_mfma_f32_16x16x32_bf16 v[2:5], v[142:145], v[178:181], v[2:5]
	s_setprio 0
.LBB0_1616:
	s_and_b64 vcc, s[38:39], s[56:57]
	v_cndmask_b32_e64 v131, v225, 0, vcc
	v_cndmask_b32_e32 v130, v224, v198, vcc
	v_lshl_add_u64 v[236:237], s[52:53], 0, v[130:131]
	s_barrier
	s_mov_b32 m0, s9
	s_nop 0
	global_load_lds_dwordx4 v194, s[98:99]
	s_mov_b32 m0, s14
	s_nop 0
	global_load_lds_dwordx4 v196, s[98:99]
	v_add_u32_e32 v1, 0x18000, v232
	ds_read_b128 v[146:149], v1
	ds_read_b128 v[150:153], v1 offset:1024
	ds_read_b128 v[154:157], v1 offset:2048
	ds_read_b128 v[158:161], v1 offset:3072
	v_add_u32_e32 v1, 0x1c000, v232
	ds_read_b128 v[130:133], v1
	ds_read_b128 v[134:137], v1 offset:1024
	ds_read_b128 v[138:141], v1 offset:2048
	ds_read_b128 v[142:145], v1 offset:3072
	s_mov_b32 m0, s15
	v_lshl_add_u64 v[238:239], v[236:237], 0, v[194:195]
	s_waitcnt lgkmcnt(0)
	ds_read_b128 v[174:177], v233 offset:32768
	ds_read_b128 v[190:193], v233 offset:33792
	ds_read_b128 v[170:173], v233 offset:34816
	ds_read_b128 v[186:189], v233 offset:35840
	ds_read_b128 v[166:169], v233 offset:36864
	ds_read_b128 v[182:185], v233 offset:37888
	ds_read_b128 v[162:165], v233 offset:38912
	ds_read_b128 v[178:181], v233 offset:39936
	global_load_lds_dwordx4 v[238:239], off
	v_lshl_add_u64 v[236:237], v[236:237], 0, v[196:197]
	s_mov_b32 m0, s16
	s_nop 0
	global_load_lds_dwordx4 v[236:237], off
	s_waitcnt vmcnt(8)
	s_waitcnt lgkmcnt(0)
	s_barrier
	s_setprio 1
	s_waitcnt lgkmcnt(0)
	v_mfma_f32_16x16x32_bf16 v[126:129], v[146:149], v[174:177], v[126:129]
	v_mfma_f32_16x16x32_bf16 v[122:125], v[154:157], v[174:177], v[122:125]
	v_mfma_f32_16x16x32_bf16 v[118:121], v[146:149], v[170:173], v[118:121]
	v_mfma_f32_16x16x32_bf16 v[110:113], v[154:157], v[170:173], v[110:113]
	v_mfma_f32_16x16x32_bf16 v[102:105], v[146:149], v[166:169], v[102:105]
	v_mfma_f32_16x16x32_bf16 v[94:97], v[154:157], v[166:169], v[94:97]
	v_mfma_f32_16x16x32_bf16 v[86:89], v[146:149], v[162:165], v[86:89]
	v_mfma_f32_16x16x32_bf16 v[78:81], v[154:157], v[162:165], v[78:81]
	v_mfma_f32_16x16x32_bf16 v[126:129], v[150:153], v[190:193], v[126:129]
	v_mfma_f32_16x16x32_bf16 v[122:125], v[158:161], v[190:193], v[122:125]
	v_mfma_f32_16x16x32_bf16 v[118:121], v[150:153], v[186:189], v[118:121]
	v_mfma_f32_16x16x32_bf16 v[110:113], v[158:161], v[186:189], v[110:113]
	v_mfma_f32_16x16x32_bf16 v[102:105], v[150:153], v[182:185], v[102:105]
	v_mfma_f32_16x16x32_bf16 v[94:97], v[158:161], v[182:185], v[94:97]
	v_mfma_f32_16x16x32_bf16 v[86:89], v[150:153], v[178:181], v[86:89]
	v_mfma_f32_16x16x32_bf16 v[78:81], v[158:161], v[178:181], v[78:81]
	s_setprio 0
	s_setprio 1
	s_add_u32 s56, s50, 0x40000
	s_addc_u32 s57, s51, 0
	s_add_u32 s52, s52, 0x220000
	s_addc_u32 s53, s53, 0
	v_mfma_f32_16x16x32_bf16 v[114:117], v[130:133], v[174:177], v[114:117]
	v_mfma_f32_16x16x32_bf16 v[106:109], v[138:141], v[174:177], v[106:109]
	v_mfma_f32_16x16x32_bf16 v[98:101], v[130:133], v[170:173], v[98:101]
	v_mfma_f32_16x16x32_bf16 v[90:93], v[138:141], v[170:173], v[90:93]
	v_mfma_f32_16x16x32_bf16 v[82:85], v[130:133], v[166:169], v[82:85]
	v_mfma_f32_16x16x32_bf16 v[74:77], v[138:141], v[166:169], v[74:77]
	v_mfma_f32_16x16x32_bf16 v[70:73], v[130:133], v[162:165], v[70:73]
	v_mfma_f32_16x16x32_bf16 v[66:69], v[138:141], v[162:165], v[66:69]
	v_mfma_f32_16x16x32_bf16 v[114:117], v[134:137], v[190:193], v[114:117]
	v_mfma_f32_16x16x32_bf16 v[106:109], v[142:145], v[190:193], v[106:109]
	v_mfma_f32_16x16x32_bf16 v[98:101], v[134:137], v[186:189], v[98:101]
	v_mfma_f32_16x16x32_bf16 v[90:93], v[142:145], v[186:189], v[90:93]
	v_mfma_f32_16x16x32_bf16 v[82:85], v[134:137], v[182:185], v[82:85]
	v_mfma_f32_16x16x32_bf16 v[74:77], v[142:145], v[182:185], v[74:77]
	v_mfma_f32_16x16x32_bf16 v[70:73], v[134:137], v[178:181], v[70:73]
	v_mfma_f32_16x16x32_bf16 v[66:69], v[142:145], v[178:181], v[66:69]
	s_setprio 0
	s_barrier
	s_and_b64 vcc, exec, s[42:43]
	s_cbranch_vccnz .LBB0_1618
	ds_read_b128 v[174:177], v233 offset:49152
	ds_read_b128 v[190:193], v233 offset:50176
	ds_read_b128 v[170:173], v233 offset:51200
	ds_read_b128 v[186:189], v233 offset:52224
	ds_read_b128 v[166:169], v233 offset:53248
	ds_read_b128 v[182:185], v233 offset:54272
	ds_read_b128 v[162:165], v233 offset:55296
	ds_read_b128 v[178:181], v233 offset:56320
.LBB0_1618:
	s_mov_b32 m0, s17
	s_add_u32 s50, s50, 0x44000
	global_load_lds_dwordx4 v194, s[56:57]
	s_mov_b32 m0, s29
	s_addc_u32 s51, s51, 0
	global_load_lds_dwordx4 v196, s[56:57]
	s_mov_b32 m0, s58
	s_and_b64 vcc, exec, s[42:43]
	global_load_lds_dwordx4 v194, s[50:51]
	s_mov_b32 m0, s59
	s_nop 0
	global_load_lds_dwordx4 v196, s[50:51]
	s_mov_b64 s[100:101], s[52:53]
	s_waitcnt vmcnt(6)
	s_waitcnt lgkmcnt(0)
	s_barrier
	s_cbranch_vccnz .LBB0_1611
	s_setprio 1
	s_waitcnt lgkmcnt(0)
	v_mfma_f32_16x16x32_bf16 v[62:65], v[146:149], v[174:177], v[62:65]
	v_mfma_f32_16x16x32_bf16 v[58:61], v[154:157], v[174:177], v[58:61]
	v_mfma_f32_16x16x32_bf16 v[46:49], v[146:149], v[170:173], v[46:49]
	v_mfma_f32_16x16x32_bf16 v[42:45], v[154:157], v[170:173], v[42:45]
	v_mfma_f32_16x16x32_bf16 v[30:33], v[146:149], v[166:169], v[30:33]
	v_mfma_f32_16x16x32_bf16 v[26:29], v[154:157], v[166:169], v[26:29]
	v_mfma_f32_16x16x32_bf16 v[14:17], v[146:149], v[162:165], v[14:17]
	v_mfma_f32_16x16x32_bf16 v[10:13], v[154:157], v[162:165], v[10:13]
	v_mfma_f32_16x16x32_bf16 v[62:65], v[150:153], v[190:193], v[62:65]
	v_mfma_f32_16x16x32_bf16 v[58:61], v[158:161], v[190:193], v[58:61]
	v_mfma_f32_16x16x32_bf16 v[46:49], v[150:153], v[186:189], v[46:49]
	v_mfma_f32_16x16x32_bf16 v[42:45], v[158:161], v[186:189], v[42:45]
	v_mfma_f32_16x16x32_bf16 v[30:33], v[150:153], v[182:185], v[30:33]
	v_mfma_f32_16x16x32_bf16 v[26:29], v[158:161], v[182:185], v[26:29]
	v_mfma_f32_16x16x32_bf16 v[14:17], v[150:153], v[178:181], v[14:17]
	v_mfma_f32_16x16x32_bf16 v[10:13], v[158:161], v[178:181], v[10:13]
	s_setprio 0
	s_setprio 1
	v_mfma_f32_16x16x32_bf16 v[54:57], v[130:133], v[174:177], v[54:57]
	v_mfma_f32_16x16x32_bf16 v[50:53], v[138:141], v[174:177], v[50:53]
	v_mfma_f32_16x16x32_bf16 v[38:41], v[130:133], v[170:173], v[38:41]
	v_mfma_f32_16x16x32_bf16 v[34:37], v[138:141], v[170:173], v[34:37]
	v_mfma_f32_16x16x32_bf16 v[22:25], v[130:133], v[166:169], v[22:25]
	v_mfma_f32_16x16x32_bf16 v[18:21], v[138:141], v[166:169], v[18:21]
	v_mfma_f32_16x16x32_bf16 v[6:9], v[130:133], v[162:165], v[6:9]
	v_mfma_f32_16x16x32_bf16 v[2:5], v[138:141], v[162:165], v[2:5]
	v_mfma_f32_16x16x32_bf16 v[54:57], v[134:137], v[190:193], v[54:57]
	v_mfma_f32_16x16x32_bf16 v[50:53], v[142:145], v[190:193], v[50:53]
	v_mfma_f32_16x16x32_bf16 v[38:41], v[134:137], v[186:189], v[38:41]
	v_mfma_f32_16x16x32_bf16 v[34:37], v[142:145], v[186:189], v[34:37]
	v_mfma_f32_16x16x32_bf16 v[22:25], v[134:137], v[182:185], v[22:25]
	v_mfma_f32_16x16x32_bf16 v[18:21], v[142:145], v[182:185], v[18:21]
	v_mfma_f32_16x16x32_bf16 v[6:9], v[134:137], v[178:181], v[6:9]
	v_mfma_f32_16x16x32_bf16 v[2:5], v[142:145], v[178:181], v[2:5]
	s_setprio 0
	s_branch .LBB0_1611
